# v77 plus J-phase loops: layer-0 gamma/beta resident, row loads of both variants issued together
# baseline (speedup 1.0000x reference)
.LBB0_1705:
	s_mov_b64 s[10:11], s[0:1]
	v_mov_b32_e32 v2, v0
	s_mov_b64 s[22:23], s[44:45]
	v_mov_b32_e32 v1, v232
	s_mov_b64 s[18:19], s[46:47]
	s_add_i32 s9, s60, s8
	v_lshlrev_b32_e32 v2, 2, v1
	v_ashrrev_i32_e32 v3, 31, v2
	v_lshlrev_b64 v[4:5], 1, v[2:3]
	v_lshl_add_u64 v[8:9], s[18:19], 0, v[4:5]
	v_lshl_add_u64 v[8:9], v[8:9], 0, s[16:17]
	global_load_dwordx2 v[56:57], v[8:9], off offset:-3584
	global_load_dwordx2 v[62:63], v[8:9], off offset:-3072
	global_load_dwordx2 v[66:67], v[8:9], off offset:-2560
	global_load_dwordx2 v[10:11], v[8:9], off offset:-2048
	s_cmpk_lt_i32 s9, 0x2000
	s_cselect_b32 s24, s9, s8
	s_ashr_i32 s25, s24, 31
	s_lshl_b64 s[20:21], s[24:25], 12
	s_add_u32 s18, s18, s20
	s_addc_u32 s19, s19, s21
	v_lshl_add_u64 v[4:5], s[18:19], 0, v[4:5]
	v_lshl_add_u64 v[224:225], v[4:5], 0, s[54:55]
	global_load_dwordx2 v[92:93], v[8:9], off offset:-1536
	global_load_dwordx2 v[98:99], v[8:9], off offset:-1024
	global_load_dwordx2 v[100:101], v[8:9], off offset:-512
	global_load_dwordx2 v[108:109], v[8:9], off
	global_load_dwordx2 v[110:111], v[224:225], off
	global_load_dwordx2 v[118:119], v[224:225], off offset:512
	global_load_dwordx2 v[120:121], v[224:225], off offset:1024
	global_load_dwordx2 v[122:123], v[224:225], off offset:1536
	global_load_dwordx2 v[144:145], v[224:225], off offset:2048
	global_load_dwordx2 v[146:147], v[224:225], off offset:2560
	global_load_dwordx2 v[152:153], v[224:225], off offset:3072
	global_load_dwordx2 v[154:155], v[224:225], off offset:3584
	v_and_b32_e32 v7, 64, v249
	v_add_u32_e32 v12, 64, v7
	v_xor_b32_e32 v7, 1, v249
	s_waitcnt vmcnt(3)
	v_lshlrev_b32_e32 v68, 16, v56
	s_waitcnt vmcnt(2)
	v_lshlrev_b32_e32 v69, 16, v62
	v_and_b32_e32 v71, 0xffff0000, v62
	s_waitcnt vmcnt(0)
	v_lshlrev_b32_e32 v58, 16, v10
	v_and_b32_e32 v59, 0xffff0000, v10
	v_lshlrev_b32_e32 v60, 16, v11
	v_and_b32_e32 v61, 0xffff0000, v11
	s_nop 1
	v_mov_b64_e32 v[10:11], v[92:93]
	v_and_b32_e32 v70, 0xffff0000, v56
	v_lshlrev_b32_e32 v65, 16, v63
	v_lshlrev_b32_e32 v64, 16, v57
	v_and_b32_e32 v75, 0xffff0000, v63
	v_and_b32_e32 v74, 0xffff0000, v57
	v_pk_add_f32 v[56:57], v[64:65], v[74:75]
	v_lshlrev_b32_e32 v63, 16, v67
	v_lshlrev_b32_e32 v62, 16, v66
	v_and_b32_e32 v73, 0xffff0000, v67
	v_and_b32_e32 v72, 0xffff0000, v66
	v_add_f32_e32 v54, v58, v59
	v_add_f32_e32 v52, v60, v61
	s_waitcnt vmcnt(0)
	v_lshlrev_b32_e32 v51, 16, v10
	v_and_b32_e32 v49, 0xffff0000, v10
	v_lshlrev_b32_e32 v55, 16, v11
	v_and_b32_e32 v53, 0xffff0000, v11
	s_nop 1
	v_mov_b64_e32 v[76:77], v[98:99]
	s_nop 1
	v_mov_b64_e32 v[10:11], v[100:101]
	s_waitcnt vmcnt(0)
	v_lshlrev_b32_e32 v46, 16, v11
	s_nop 1
	v_mov_b64_e32 v[8:9], v[108:109]
	v_and_b32_e32 v47, 0xffff0000, v11
	v_lshlrev_b32_e32 v40, 16, v10
	v_and_b32_e32 v41, 0xffff0000, v10
	v_add_f32_e32 v44, v40, v41
	v_add_f32_e32 v42, v46, v47
	s_waitcnt vmcnt(0)
	v_lshlrev_b32_e32 v38, 16, v8
	v_and_b32_e32 v39, 0xffff0000, v8
	v_lshlrev_b32_e32 v45, 16, v9
	v_and_b32_e32 v43, 0xffff0000, v9
	v_lshl_add_u64 v[8:9], v[4:5], 0, s[54:55]
	v_add_co_u32_e32 v4, vcc, s27, v4
	s_nop 1
	v_addc_co_u32_e32 v5, vcc, 0, v5, vcc
	s_nop 1
	v_mov_b64_e32 v[34:35], v[110:111]
	s_nop 1
	v_mov_b64_e32 v[36:37], v[118:119]
	s_nop 1
	v_mov_b64_e32 v[32:33], v[120:121]
	s_nop 0
	s_nop 1
	v_mov_b64_e32 v[4:5], v[122:123]
	v_cmp_lt_i32_e32 vcc, v7, v12
	s_waitcnt vmcnt(0)
	v_lshlrev_b32_e32 v26, 16, v4
	v_and_b32_e32 v27, 0xffff0000, v4
	v_lshlrev_b32_e32 v28, 16, v5
	v_and_b32_e32 v29, 0xffff0000, v5
	s_nop 1
	v_mov_b64_e32 v[4:5], v[144:145]
	v_cndmask_b32_e32 v7, v249, v7, vcc
	v_lshlrev_b32_e32 v7, 2, v7
	v_add_f32_e32 v24, v26, v27
	s_waitcnt vmcnt(0)
	v_lshlrev_b32_e32 v21, 16, v4
	v_and_b32_e32 v19, 0xffff0000, v4
	v_lshlrev_b32_e32 v25, 16, v5
	v_and_b32_e32 v23, 0xffff0000, v5
	s_nop 1
	v_mov_b64_e32 v[30:31], v[146:147]
	s_nop 1
	v_mov_b64_e32 v[4:5], v[152:153]
	s_load_dwordx4 s[28:31], s[10:11], 0xb0
	s_waitcnt lgkmcnt(0)
	s_add_u32 s20, s28, 0x2000
	s_addc_u32 s21, s29, 0
	s_add_u32 s18, s30, 0x2000
	s_addc_u32 s19, s31, 0
	s_waitcnt vmcnt(0)
	v_lshlrev_b32_e32 v14, 16, v4
	v_and_b32_e32 v15, 0xffff0000, v4
	v_lshlrev_b32_e32 v16, 16, v5
	v_and_b32_e32 v17, 0xffff0000, v5
	s_nop 1
	v_mov_b64_e32 v[4:5], v[154:155]
	s_waitcnt vmcnt(0)
	v_lshlrev_b32_e32 v8, 16, v4
	v_and_b32_e32 v9, 0xffff0000, v4
	v_lshlrev_b32_e32 v13, 16, v5
	v_and_b32_e32 v11, 0xffff0000, v5
	v_pk_add_f32 v[4:5], v[68:69], v[70:71]
	s_nop 0
	v_pk_add_f32 v[4:5], v[4:5], v[56:57]
	v_pk_add_f32 v[56:57], v[54:55], v[52:53]
	v_add_f32_e32 v4, 0, v4
	v_add_f32_e32 v50, v4, v5
	v_pk_add_f32 v[4:5], v[62:63], v[72:73]
	s_nop 0
	v_pk_add_f32 v[4:5], v[4:5], v[4:5] op_sel:[0,1] op_sel_hi:[1,0]
	s_nop 0
	v_mov_b32_e32 v5, v49
	v_pk_add_f32 v[4:5], v[50:51], v[4:5]
	s_nop 0
	v_pk_add_f32 v[66:67], v[4:5], v[56:57]
	v_lshlrev_b32_e32 v57, 16, v77
	v_lshlrev_b32_e32 v56, 16, v76
	v_and_b32_e32 v5, 0xffff0000, v77
	v_and_b32_e32 v4, 0xffff0000, v76
	v_pk_add_f32 v[76:77], v[56:57], v[4:5]
	v_pk_add_f32 v[66:67], v[66:67], v[66:67] op_sel:[0,1] op_sel_hi:[1,0]
	v_pk_add_f32 v[76:77], v[76:77], v[76:77] op_sel:[0,1] op_sel_hi:[1,0]
	v_mov_b32_e32 v67, v38
	v_mov_b32_e32 v77, v39
	v_pk_add_f32 v[66:67], v[66:67], v[76:77]
	v_pk_add_f32 v[76:77], v[44:45], v[42:43]
	v_lshlrev_b32_e32 v44, 16, v35
	v_pk_add_f32 v[66:67], v[66:67], v[76:77]
	s_nop 0
	v_add_f32_e32 v10, v66, v67
	ds_bpermute_b32 v18, v7, v10
	s_waitcnt lgkmcnt(0)
	v_add_f32_e32 v10, v10, v18
	v_xor_b32_e32 v18, 2, v249
	v_cmp_lt_i32_e32 vcc, v18, v12
	s_nop 1
	v_cndmask_b32_e32 v18, v249, v18, vcc
	v_lshlrev_b32_e32 v18, 2, v18
	ds_bpermute_b32 v20, v18, v10
	s_waitcnt lgkmcnt(0)
	v_add_f32_e32 v10, v10, v20
	v_xor_b32_e32 v20, 4, v249
	v_cmp_lt_i32_e32 vcc, v20, v12
	s_nop 1
	v_cndmask_b32_e32 v20, v249, v20, vcc
	v_lshlrev_b32_e32 v50, 2, v20
	ds_bpermute_b32 v20, v50, v10
	s_waitcnt lgkmcnt(0)
	v_add_f32_e32 v10, v10, v20
	v_xor_b32_e32 v20, 8, v249
	v_cmp_lt_i32_e32 vcc, v20, v12
	s_nop 1
	v_cndmask_b32_e32 v20, v249, v20, vcc
	v_lshlrev_b32_e32 v54, 2, v20
	ds_bpermute_b32 v20, v54, v10
	s_waitcnt lgkmcnt(0)
	v_add_f32_e32 v10, v10, v20
	v_xor_b32_e32 v20, 16, v249
	v_cmp_lt_i32_e32 vcc, v20, v12
	s_nop 1
	v_cndmask_b32_e32 v20, v249, v20, vcc
	v_lshlrev_b32_e32 v82, 2, v20
	ds_bpermute_b32 v20, v82, v10
	s_waitcnt lgkmcnt(0)
	v_add_f32_e32 v10, v10, v20
	v_xor_b32_e32 v20, 32, v249
	v_cmp_lt_i32_e32 vcc, v20, v12
	s_nop 1
	v_cndmask_b32_e32 v12, v249, v20, vcc
	v_lshlrev_b32_e32 v84, 2, v12
	ds_bpermute_b32 v12, v84, v10
	s_waitcnt lgkmcnt(0)
	v_add_f32_e32 v12, v10, v12
	v_fmac_f32_e32 v70, 0xba000000, v12
	v_fmac_f32_e32 v71, 0xba000000, v12
	v_fmac_f32_e32 v74, 0xba000000, v12
	v_fmac_f32_e32 v68, 0xba000000, v12
	v_fmac_f32_e32 v75, 0xba000000, v12
	v_fmac_f32_e32 v69, 0xba000000, v12
	v_mov_b32_e32 v67, v71
	v_mov_b32_e32 v79, v70
	v_pk_mul_f32 v[70:71], v[70:71], v[70:71]
	v_fmac_f32_e32 v64, 0xba000000, v12
	v_fmac_f32_e32 v65, 0xba000000, v12
	v_mov_b32_e32 v66, v69
	v_mov_b32_e32 v78, v68
	v_pk_fma_f32 v[68:69], v[68:69], v[68:69], v[70:71]
	v_mov_b32_e32 v71, v75
	v_mov_b32_e32 v81, v74
	v_pk_mul_f32 v[74:75], v[74:75], v[74:75]
	v_mov_b32_e32 v70, v65
	v_mov_b32_e32 v80, v64
	v_pk_fma_f32 v[64:65], v[64:65], v[64:65], v[74:75]
	v_fmac_f32_e32 v72, 0xba000000, v12
	v_fmac_f32_e32 v73, 0xba000000, v12
	v_fmac_f32_e32 v63, 0xba000000, v12
	v_pk_add_f32 v[64:65], v[68:69], v[64:65]
	v_fmac_f32_e32 v62, 0xba000000, v12
	v_mov_b32_e32 v68, v63
	v_mov_b32_e32 v69, v73
	v_mov_b32_e32 v63, v72
	v_pk_mul_f32 v[74:75], v[68:69], v[68:69]
	v_pk_mul_f32 v[72:73], v[62:63], v[62:63]
	v_fmac_f32_e32 v58, 0xba000000, v12
	v_pk_mov_b32 v[76:77], v[72:73], v[74:75] op_sel:[1,0]
	v_mov_b32_e32 v73, v75
	v_fmac_f32_e32 v59, 0xba000000, v12
	v_fmac_f32_e32 v60, 0xba000000, v12
	v_mul_f32_e32 v10, v58, v58
	v_pk_add_f32 v[72:73], v[76:77], v[72:73]
	v_fmac_f32_e32 v61, 0xba000000, v12
	v_pk_fma_f32 v[74:75], v[58:59], v[58:59], v[10:11] op_sel_hi:[1,1,0]
	v_mul_f32_e32 v10, v60, v60
	v_pk_add_f32 v[64:65], v[64:65], v[64:65] op_sel_hi:[0,1]
	v_pk_add_f32 v[72:73], v[72:73], v[72:73] op_sel_hi:[0,1]
	v_pk_fma_f32 v[76:77], v[60:61], v[60:61], v[10:11] op_sel_hi:[1,1,0]
	v_fmac_f32_e32 v53, 0xba000000, v12
	v_fmac_f32_e32 v55, 0xba000000, v12
	v_fmac_f32_e32 v49, 0xba000000, v12
	v_fmac_f32_e32 v51, 0xba000000, v12
	v_mul_f32_e32 v74, v51, v51
	v_mul_f32_e32 v76, v49, v49
	v_mul_f32_e32 v72, v55, v55
	v_mul_f32_e32 v64, v53, v53
	v_pk_add_f32 v[74:75], v[74:75], v[76:77]
	v_pk_add_f32 v[64:65], v[72:73], v[64:65]
	v_fmac_f32_e32 v4, 0xba000000, v12
	v_pk_add_f32 v[64:65], v[74:75], v[64:65]
	v_fmac_f32_e32 v5, 0xba000000, v12
	v_fmac_f32_e32 v57, 0xba000000, v12
	v_pk_add_f32 v[72:73], v[64:65], v[64:65] op_sel_hi:[0,1]
	v_fmac_f32_e32 v56, 0xba000000, v12
	v_mov_b32_e32 v64, v57
	v_mov_b32_e32 v65, v5
	v_mov_b32_e32 v57, v4
	v_pk_mul_f32 v[74:75], v[64:65], v[64:65]
	v_pk_mul_f32 v[4:5], v[56:57], v[56:57]
	v_fmac_f32_e32 v40, 0xba000000, v12
	v_pk_mov_b32 v[76:77], v[4:5], v[74:75] op_sel:[1,0]
	v_mov_b32_e32 v5, v75
	v_pk_add_f32 v[4:5], v[76:77], v[4:5]
	v_fmac_f32_e32 v41, 0xba000000, v12
	v_pk_add_f32 v[4:5], v[4:5], v[4:5] op_sel_hi:[0,1]
	v_fmac_f32_e32 v46, 0xba000000, v12
	v_mul_f32_e32 v4, v40, v40
	v_fmac_f32_e32 v47, 0xba000000, v12
	v_pk_fma_f32 v[74:75], v[40:41], v[40:41], v[4:5] op_sel_hi:[1,1,0]
	v_mul_f32_e32 v4, v46, v46
	v_pk_fma_f32 v[76:77], v[46:47], v[46:47], v[4:5] op_sel_hi:[1,1,0]
	v_fmac_f32_e32 v43, 0xba000000, v12
	v_fmac_f32_e32 v45, 0xba000000, v12
	v_fmac_f32_e32 v39, 0xba000000, v12
	v_fmac_f32_e32 v38, 0xba000000, v12
	v_mul_f32_e32 v74, v38, v38
	v_mul_f32_e32 v76, v39, v39
	v_mul_f32_e32 v4, v45, v45
	v_mul_f32_e32 v72, v43, v43
	v_pk_add_f32 v[74:75], v[74:75], v[76:77]
	v_pk_add_f32 v[4:5], v[4:5], v[72:73]
	v_lshlrev_b64 v[72:73], 2, v[2:3]
	v_pk_add_f32 v[4:5], v[74:75], v[4:5]
	v_lshl_add_u64 v[76:77], s[20:21], 0, v[72:73]
	v_add_f32_e32 v4, v4, v5
	ds_bpermute_b32 v5, v7, v4
	v_lshl_add_u64 v[74:75], s[18:19], 0, v[72:73]
	s_nop 1
	v_mov_b64_e32 v[86:87], v[212:213]
	v_mov_b64_e32 v[88:89], v[214:215]
	v_lshl_add_u64 v[72:73], s[22:23], 0, v[72:73]
	v_lshl_add_u64 v[72:73], v[72:73], 0, s[14:15]
	s_waitcnt lgkmcnt(0)
	v_add_f32_e32 v4, v4, v5
	ds_bpermute_b32 v5, v18, v4
	v_mov_b32_e32 v52, v55
	v_mov_b32_e32 v48, v51
	v_mov_b32_e32 v42, v45
	v_lshlrev_b32_e32 v45, 16, v37
	s_waitcnt lgkmcnt(0)
	v_add_f32_e32 v4, v4, v5
	ds_bpermute_b32 v5, v50, v4
	s_waitcnt lgkmcnt(0)
	v_add_f32_e32 v4, v4, v5
	ds_bpermute_b32 v5, v54, v4
	s_waitcnt lgkmcnt(0)
	v_add_f32_e32 v4, v4, v5
	ds_bpermute_b32 v5, v82, v4
	s_waitcnt lgkmcnt(0)
	v_add_f32_e32 v4, v4, v5
	ds_bpermute_b32 v5, v84, v4
	s_waitcnt lgkmcnt(0)
	v_add_f32_e32 v4, v4, v5
	v_fmamk_f32 v4, v4, 0x3a000000, v250
	v_cmp_gt_f32_e32 vcc, s96, v4
	v_mul_f32_e32 v5, 0x4f800000, v4
	s_nop 0
	v_cndmask_b32_e32 v4, v4, v5, vcc
	v_sqrt_f32_e32 v5, v4
	s_nop 0
	v_add_u32_e32 v10, -1, v5
	v_fma_f32 v12, -v10, v5, v4
	v_cmp_ge_f32_e64 s[10:11], 0, v12
	v_add_u32_e32 v12, 1, v5
	s_nop 0
	v_cndmask_b32_e64 v10, v5, v10, s[10:11]
	v_fma_f32 v5, -v12, v5, v4
	v_cmp_lt_f32_e64 s[10:11], 0, v5
	s_nop 1
	v_cndmask_b32_e64 v5, v10, v12, s[10:11]
	v_mul_f32_e32 v10, 0x37800000, v5
	v_cndmask_b32_e32 v5, v5, v10, vcc
	v_cmp_class_f32_e32 vcc, v4, v251
	s_nop 1
	v_cndmask_b32_e32 v4, v5, v4, vcc
	v_div_scale_f32 v5, s[10:11], v4, v4, 1.0
	v_rcp_f32_e32 v10, v5
	s_lshl_b64 s[10:11], s[24:25], 13
	s_add_u32 s22, s22, s10
	s_addc_u32 s23, s23, s11
	v_fma_f32 v12, -v5, v10, 1.0
	v_fmac_f32_e32 v10, v12, v10
	v_div_scale_f32 v12, vcc, 1.0, v4, 1.0
	v_mul_f32_e32 v20, v12, v10
	v_fma_f32 v22, -v5, v20, v12
	v_fmac_f32_e32 v20, v22, v10
	v_fma_f32 v5, -v5, v20, v12
	v_div_fmas_f32 v5, v5, v10, v20
	v_div_fixup_f32 v10, v5, v4, 1.0
	s_nop 1
	v_mov_b64_e32 v[2:3], v[180:181]
	v_mov_b64_e32 v[4:5], v[182:183]
	v_pk_mul_f32 v[78:79], v[78:79], v[10:11] op_sel_hi:[1,0]
	v_pk_mul_f32 v[80:81], v[80:81], v[10:11] op_sel_hi:[1,0]
	v_pk_mul_f32 v[70:71], v[70:71], v[10:11] op_sel_hi:[1,0]
	v_pk_mul_f32 v[66:67], v[66:67], v[10:11] op_sel_hi:[1,0]
	v_pk_mul_f32 v[62:63], v[62:63], v[10:11] op_sel_hi:[1,0]
	v_pk_mul_f32 v[60:61], v[60:61], v[10:11] op_sel_hi:[1,0]
	v_pk_mul_f32 v[58:59], v[58:59], v[10:11] op_sel_hi:[1,0]
	v_pk_mul_f32 v[52:53], v[52:53], v[10:11] op_sel_hi:[1,0]
	v_pk_mul_f32 v[48:49], v[48:49], v[10:11] op_sel_hi:[1,0]
	v_pk_mul_f32 v[46:47], v[46:47], v[10:11] op_sel_hi:[1,0]
	v_pk_mul_f32 v[40:41], v[40:41], v[10:11] op_sel_hi:[1,0]
	v_pk_mul_f32 v[38:39], v[38:39], v[10:11] op_sel_hi:[1,0]
	v_add_f32_e32 v22, v28, v29
	v_add_f32_e32 v12, v14, v15
	s_add_i32 s8, s8, s26
	s_add_u32 s16, s16, s34
	s_addc_u32 s17, s17, s35
	s_add_u32 s14, s14, s36
	s_addc_u32 s15, s15, s37
	s_cmpk_lt_i32 s8, 0x2000
	s_waitcnt vmcnt(0)
	v_pk_fma_f32 v[2:3], v[2:3], v[78:79], v[86:87]
	v_add_co_u32_e32 v78, vcc, s38, v72
	v_pk_fma_f32 v[4:5], v[4:5], v[80:81], v[88:89]
	s_nop 0
	v_addc_co_u32_e32 v79, vcc, -1, v73, vcc
	global_store_dwordx4 v[78:79], v[2:5], off offset:-3072
	s_nop 1
	v_mov_b64_e32 v[2:3], v[184:185]
	v_mov_b64_e32 v[4:5], v[186:187]
	s_nop 0
	s_nop 1
	v_mov_b64_e32 v[86:87], v[216:217]
	v_mov_b64_e32 v[88:89], v[218:219]
	s_waitcnt vmcnt(0)
	v_pk_fma_f32 v[2:3], v[2:3], v[66:67], v[86:87]
	v_pk_fma_f32 v[4:5], v[4:5], v[70:71], v[88:89]
	global_store_dwordx4 v[78:79], v[2:5], off offset:-2048
	s_nop 1
	v_mov_b64_e32 v[2:3], v[188:189]
	v_mov_b64_e32 v[4:5], v[190:191]
	s_nop 1
	v_mov_b64_e32 v[86:87], v[220:221]
	v_mov_b64_e32 v[88:89], v[222:223]
	v_pk_mul_f32 v[66:67], v[68:69], v[10:11] op_sel_hi:[1,0]
	s_waitcnt vmcnt(0)
	v_pk_fma_f32 v[2:3], v[2:3], v[62:63], v[86:87]
	v_pk_fma_f32 v[4:5], v[4:5], v[66:67], v[88:89]
	global_store_dwordx4 v[78:79], v[2:5], off offset:-1024
	s_nop 1
	v_mov_b64_e32 v[2:3], v[192:193]
	v_mov_b64_e32 v[4:5], v[194:195]
	s_nop 0
	s_nop 1
	v_mov_b64_e32 v[66:67], v[236:237]
	v_mov_b64_e32 v[68:69], v[238:239]
	v_add_co_u32_e32 v62, vcc, s82, v76
	s_waitcnt vmcnt(0)
	v_pk_fma_f32 v[2:3], v[2:3], v[58:59], v[66:67]
	v_pk_fma_f32 v[4:5], v[4:5], v[60:61], v[68:69]
	v_addc_co_u32_e32 v63, vcc, 0, v77, vcc
	global_store_dwordx4 v[72:73], v[2:5], off offset:-4096
	v_add_co_u32_e32 v66, vcc, s82, v74
	s_nop 1
	v_mov_b64_e32 v[2:3], v[196:197]
	v_mov_b64_e32 v[4:5], v[198:199]
	s_nop 0
	v_addc_co_u32_e32 v67, vcc, 0, v75, vcc
	s_nop 1
	v_mov_b64_e32 v[58:59], v[240:241]
	v_mov_b64_e32 v[60:61], v[242:243]
	s_waitcnt vmcnt(0)
	v_pk_fma_f32 v[2:3], v[2:3], v[48:49], v[58:59]
	v_pk_fma_f32 v[4:5], v[4:5], v[52:53], v[60:61]
	global_store_dwordx4 v[72:73], v[2:5], off offset:-3072
	s_nop 1
	v_mov_b64_e32 v[2:3], v[200:201]
	v_mov_b64_e32 v[4:5], v[202:203]
	s_nop 0
	s_nop 1
	v_mov_b64_e32 v[58:59], v[128:129]
	v_mov_b64_e32 v[60:61], v[130:131]
	v_pk_mul_f32 v[48:49], v[64:65], v[10:11] op_sel_hi:[1,0]
	v_pk_mul_f32 v[52:53], v[56:57], v[10:11] op_sel_hi:[1,0]
	s_waitcnt vmcnt(0)
	v_pk_fma_f32 v[4:5], v[4:5], v[48:49], v[60:61]
	v_pk_fma_f32 v[2:3], v[2:3], v[52:53], v[58:59]
	global_store_dwordx4 v[72:73], v[2:5], off offset:-2048
	s_nop 1
	v_mov_b64_e32 v[2:3], v[204:205]
	v_mov_b64_e32 v[4:5], v[206:207]
	s_nop 1
	v_mov_b64_e32 v[56:57], v[132:133]
	v_mov_b64_e32 v[58:59], v[134:135]
	s_waitcnt vmcnt(0)
	v_pk_fma_f32 v[2:3], v[2:3], v[40:41], v[56:57]
	v_pk_fma_f32 v[4:5], v[4:5], v[46:47], v[58:59]
	global_store_dwordx4 v[72:73], v[2:5], off offset:-1024
	s_nop 1
	v_mov_b64_e32 v[2:3], v[208:209]
	v_mov_b64_e32 v[4:5], v[210:211]
	s_nop 0
	s_nop 1
	v_mov_b64_e32 v[46:47], v[140:141]
	v_mov_b64_e32 v[48:49], v[142:143]
	v_pk_mul_f32 v[40:41], v[42:43], v[10:11] op_sel_hi:[1,0]
	v_and_b32_e32 v43, 0xffff0000, v31
	v_and_b32_e32 v42, 0xffff0000, v30
	v_add_f32_e32 v10, v16, v17
	s_waitcnt vmcnt(0)
	v_pk_fma_f32 v[2:3], v[38:39], v[2:3], v[46:47]
	v_pk_fma_f32 v[4:5], v[40:41], v[4:5], v[48:49]
	v_lshlrev_b32_e32 v38, 16, v34
	v_lshlrev_b32_e32 v39, 16, v36
	v_and_b32_e32 v47, 0xffff0000, v36
	v_and_b32_e32 v46, 0xffff0000, v34
	v_and_b32_e32 v49, 0xffff0000, v37
	v_and_b32_e32 v48, 0xffff0000, v35
	global_store_dwordx4 v[72:73], v[2:5], off
	v_and_b32_e32 v41, 0xffff0000, v33
	v_and_b32_e32 v40, 0xffff0000, v32
	v_pk_add_f32 v[2:3], v[38:39], v[46:47]
	v_pk_add_f32 v[4:5], v[44:45], v[48:49]
	s_nop 0
	v_pk_add_f32 v[2:3], v[2:3], v[4:5]
	v_lshlrev_b32_e32 v5, 16, v33
	v_add_f32_e32 v2, 0, v2
	v_lshlrev_b32_e32 v4, 16, v32
	v_add_f32_e32 v20, v2, v3
	v_pk_add_f32 v[2:3], v[4:5], v[40:41]
	v_pk_add_f32 v[32:33], v[24:25], v[22:23]
	v_pk_add_f32 v[2:3], v[2:3], v[2:3] op_sel:[0,1] op_sel_hi:[1,0]
	s_nop 0
	v_mov_b32_e32 v3, v19
	v_pk_add_f32 v[2:3], v[20:21], v[2:3]
	s_nop 0
	v_pk_add_f32 v[32:33], v[2:3], v[32:33]
	v_lshlrev_b32_e32 v3, 16, v31
	v_lshlrev_b32_e32 v2, 16, v30
	v_pk_add_f32 v[30:31], v[2:3], v[42:43]
	v_pk_add_f32 v[32:33], v[32:33], v[32:33] op_sel:[0,1] op_sel_hi:[1,0]
	v_pk_add_f32 v[30:31], v[30:31], v[30:31] op_sel:[0,1] op_sel_hi:[1,0]
	v_mov_b32_e32 v33, v8
	v_mov_b32_e32 v31, v9
	v_pk_add_f32 v[30:31], v[32:33], v[30:31]
	v_pk_add_f32 v[32:33], v[12:13], v[10:11]
	s_nop 0
	v_pk_add_f32 v[30:31], v[30:31], v[32:33]
	s_nop 0
	v_add_f32_e32 v10, v30, v31
	ds_bpermute_b32 v12, v7, v10
	s_waitcnt lgkmcnt(0)
	v_add_f32_e32 v10, v10, v12
	ds_bpermute_b32 v12, v18, v10
	s_waitcnt lgkmcnt(0)
	v_add_f32_e32 v10, v10, v12
	ds_bpermute_b32 v12, v50, v10
	s_waitcnt lgkmcnt(0)
	v_add_f32_e32 v10, v10, v12
	ds_bpermute_b32 v12, v54, v10
	s_waitcnt lgkmcnt(0)
	v_add_f32_e32 v10, v10, v12
	ds_bpermute_b32 v12, v82, v10
	s_waitcnt lgkmcnt(0)
	v_add_f32_e32 v10, v10, v12
	ds_bpermute_b32 v12, v84, v10
	s_waitcnt lgkmcnt(0)
	v_add_f32_e32 v12, v10, v12
	v_fmac_f32_e32 v48, 0xba000000, v12
	v_fmac_f32_e32 v46, 0xba000000, v12
	v_fmac_f32_e32 v49, 0xba000000, v12
	v_fmac_f32_e32 v47, 0xba000000, v12
	v_fmac_f32_e32 v44, 0xba000000, v12
	v_fmac_f32_e32 v38, 0xba000000, v12
	v_fmac_f32_e32 v45, 0xba000000, v12
	v_fmac_f32_e32 v39, 0xba000000, v12
	v_mov_b32_e32 v31, v47
	v_mov_b32_e32 v35, v46
	v_pk_mul_f32 v[32:33], v[46:47], v[46:47]
	v_pk_mul_f32 v[46:47], v[48:49], v[48:49]
	v_mov_b32_e32 v30, v39
	v_mov_b32_e32 v34, v38
	v_pk_fma_f32 v[38:39], v[38:39], v[38:39], v[32:33]
	v_mov_b32_e32 v32, v45
	v_mov_b32_e32 v36, v44
	v_pk_fma_f32 v[44:45], v[44:45], v[44:45], v[46:47]
	v_fmac_f32_e32 v40, 0xba000000, v12
	v_pk_add_f32 v[38:39], v[38:39], v[44:45]
	v_fmac_f32_e32 v41, 0xba000000, v12
	v_fmac_f32_e32 v5, 0xba000000, v12
	v_pk_add_f32 v[44:45], v[38:39], v[38:39] op_sel_hi:[0,1]
	v_fmac_f32_e32 v4, 0xba000000, v12
	v_mov_b32_e32 v38, v5
	v_mov_b32_e32 v39, v41
	v_mov_b32_e32 v5, v40
	v_pk_mul_f32 v[46:47], v[38:39], v[38:39]
	v_pk_mul_f32 v[40:41], v[4:5], v[4:5]
	v_fmac_f32_e32 v26, 0xba000000, v12
	v_mov_b32_e32 v33, v49
	v_mov_b32_e32 v37, v48
	v_pk_mov_b32 v[48:49], v[40:41], v[46:47] op_sel:[1,0]
	v_mov_b32_e32 v41, v47
	v_fmac_f32_e32 v27, 0xba000000, v12
	v_fmac_f32_e32 v28, 0xba000000, v12
	v_mul_f32_e32 v10, v26, v26
	v_pk_add_f32 v[40:41], v[48:49], v[40:41]
	v_fmac_f32_e32 v29, 0xba000000, v12
	v_pk_fma_f32 v[46:47], v[26:27], v[26:27], v[10:11] op_sel_hi:[1,1,0]
	v_mul_f32_e32 v10, v28, v28
	v_pk_add_f32 v[40:41], v[40:41], v[40:41] op_sel_hi:[0,1]
	v_pk_fma_f32 v[48:49], v[28:29], v[28:29], v[10:11] op_sel_hi:[1,1,0]
	v_fmac_f32_e32 v23, 0xba000000, v12
	v_fmac_f32_e32 v25, 0xba000000, v12
	v_fmac_f32_e32 v19, 0xba000000, v12
	v_fmac_f32_e32 v21, 0xba000000, v12
	v_mul_f32_e32 v46, v21, v21
	v_mul_f32_e32 v48, v19, v19
	v_mul_f32_e32 v40, v25, v25
	v_mul_f32_e32 v44, v23, v23
	v_pk_add_f32 v[46:47], v[46:47], v[48:49]
	v_pk_add_f32 v[40:41], v[40:41], v[44:45]
	v_fmac_f32_e32 v42, 0xba000000, v12
	v_pk_add_f32 v[40:41], v[46:47], v[40:41]
	v_fmac_f32_e32 v43, 0xba000000, v12
	v_fmac_f32_e32 v3, 0xba000000, v12
	v_pk_add_f32 v[44:45], v[40:41], v[40:41] op_sel_hi:[0,1]
	v_fmac_f32_e32 v2, 0xba000000, v12
	v_mov_b32_e32 v40, v3
	v_mov_b32_e32 v41, v43
	v_mov_b32_e32 v3, v42
	v_pk_mul_f32 v[46:47], v[40:41], v[40:41]
	v_pk_mul_f32 v[42:43], v[2:3], v[2:3]
	v_fmac_f32_e32 v14, 0xba000000, v12
	v_pk_mov_b32 v[48:49], v[42:43], v[46:47] op_sel:[1,0]
	v_mov_b32_e32 v43, v47
	v_fmac_f32_e32 v15, 0xba000000, v12
	v_fmac_f32_e32 v16, 0xba000000, v12
	v_mul_f32_e32 v10, v14, v14
	v_pk_add_f32 v[42:43], v[48:49], v[42:43]
	v_fmac_f32_e32 v17, 0xba000000, v12
	v_pk_fma_f32 v[46:47], v[14:15], v[14:15], v[10:11] op_sel_hi:[1,1,0]
	v_mul_f32_e32 v10, v16, v16
	v_pk_add_f32 v[42:43], v[42:43], v[42:43] op_sel_hi:[0,1]
	v_pk_fma_f32 v[48:49], v[16:17], v[16:17], v[10:11] op_sel_hi:[1,1,0]
	v_fmac_f32_e32 v11, 0xba000000, v12
	v_fmac_f32_e32 v13, 0xba000000, v12
	v_fmac_f32_e32 v9, 0xba000000, v12
	v_fmac_f32_e32 v8, 0xba000000, v12
	v_mul_f32_e32 v46, v8, v8
	v_mul_f32_e32 v48, v9, v9
	v_mul_f32_e32 v42, v13, v13
	v_mul_f32_e32 v44, v11, v11
	v_pk_add_f32 v[46:47], v[46:47], v[48:49]
	v_pk_add_f32 v[42:43], v[42:43], v[44:45]
	s_nop 0
	v_pk_add_f32 v[42:43], v[46:47], v[42:43]
	s_nop 0
	v_add_f32_e32 v10, v42, v43
	ds_bpermute_b32 v7, v7, v10
	v_lshlrev_b32_e32 v42, 2, v1
	v_ashrrev_i32_e32 v43, 31, v42
	s_waitcnt lgkmcnt(0)
	v_add_f32_e32 v7, v10, v7
	ds_bpermute_b32 v10, v18, v7
	s_waitcnt lgkmcnt(0)
	v_add_f32_e32 v7, v7, v10
	ds_bpermute_b32 v10, v50, v7
	s_waitcnt lgkmcnt(0)
	v_add_f32_e32 v7, v7, v10
	ds_bpermute_b32 v10, v54, v7
	v_lshlrev_b64 v[54:55], 2, v[42:43]
	v_lshl_add_u64 v[44:45], s[20:21], 0, v[54:55]
	v_lshl_add_u64 v[42:43], s[18:19], 0, v[54:55]
	s_nop 1
	v_mov_b64_e32 v[46:47], v[180:181]
	v_mov_b64_e32 v[48:49], v[182:183]
	s_nop 1
	v_mov_b64_e32 v[50:51], v[212:213]
	v_mov_b64_e32 v[52:53], v[214:215]
	s_waitcnt lgkmcnt(0)
	v_add_f32_e32 v7, v7, v10
	ds_bpermute_b32 v10, v82, v7
	s_waitcnt lgkmcnt(0)
	v_add_f32_e32 v7, v7, v10
	ds_bpermute_b32 v10, v84, v7
	s_waitcnt lgkmcnt(0)
	v_add_f32_e32 v7, v7, v10
	v_fmamk_f32 v7, v7, 0x3a000000, v250
	v_cmp_gt_f32_e32 vcc, s96, v7
	v_mul_f32_e32 v10, 0x4f800000, v7
	s_nop 0
	v_cndmask_b32_e32 v7, v7, v10, vcc
	v_sqrt_f32_e32 v10, v7
	s_nop 0
	v_add_u32_e32 v12, -1, v10
	v_fma_f32 v18, -v12, v10, v7
	v_cmp_ge_f32_e64 s[10:11], 0, v18
	v_add_u32_e32 v18, 1, v10
	s_nop 0
	v_cndmask_b32_e64 v12, v10, v12, s[10:11]
	v_fma_f32 v10, -v18, v10, v7
	v_cmp_lt_f32_e64 s[10:11], 0, v10
	s_nop 1
	v_cndmask_b32_e64 v10, v12, v18, s[10:11]
	v_mul_f32_e32 v12, 0x37800000, v10
	v_cndmask_b32_e32 v10, v10, v12, vcc
	v_cmp_class_f32_e32 vcc, v7, v251
	s_nop 1
	v_cndmask_b32_e32 v7, v10, v7, vcc
	v_div_scale_f32 v10, s[10:11], v7, v7, 1.0
	v_rcp_f32_e32 v12, v10
	s_nop 0
	v_fma_f32 v18, -v10, v12, 1.0
	v_fmac_f32_e32 v12, v18, v12
	v_div_scale_f32 v18, vcc, 1.0, v7, 1.0
	v_mul_f32_e32 v20, v18, v12
	v_fma_f32 v22, -v10, v20, v18
	v_fmac_f32_e32 v20, v22, v12
	v_fma_f32 v10, -v10, v20, v18
	v_div_fmas_f32 v10, v10, v12, v20
	v_div_fixup_f32 v12, v10, v7, 1.0
	v_pk_mul_f32 v[36:37], v[36:37], v[12:13] op_sel_hi:[1,0]
	v_pk_mul_f32 v[34:35], v[34:35], v[12:13] op_sel_hi:[1,0]
	v_pk_mul_f32 v[32:33], v[32:33], v[12:13] op_sel_hi:[1,0]
	v_pk_mul_f32 v[30:31], v[30:31], v[12:13] op_sel_hi:[1,0]
	v_pk_mul_f32 v[38:39], v[38:39], v[12:13] op_sel_hi:[1,0]
	v_pk_mul_f32 v[4:5], v[4:5], v[12:13] op_sel_hi:[1,0]
	v_pk_mul_f32 v[26:27], v[26:27], v[12:13] op_sel_hi:[1,0]
	v_mov_b32_e32 v18, v21
	v_mov_b32_e32 v22, v25
	v_pk_mul_f32 v[18:19], v[18:19], v[12:13] op_sel_hi:[1,0]
	v_pk_mul_f32 v[2:3], v[2:3], v[12:13] op_sel_hi:[1,0]
	v_pk_mul_f32 v[16:17], v[16:17], v[12:13] op_sel_hi:[1,0]
	v_pk_mul_f32 v[14:15], v[14:15], v[12:13] op_sel_hi:[1,0]
	v_mov_b32_e32 v10, v13
	v_pk_mul_f32 v[10:11], v[10:11], v[12:13] op_sel_hi:[1,0]
	v_pk_mul_f32 v[8:9], v[8:9], v[12:13] op_sel_hi:[1,0]
	s_waitcnt vmcnt(0)
	v_pk_fma_f32 v[34:35], v[46:47], v[34:35], v[50:51]
	v_pk_fma_f32 v[36:37], v[48:49], v[36:37], v[52:53]
	v_lshl_add_u64 v[50:51], s[22:23], 0, v[54:55]
	global_store_dwordx4 v[50:51], v[34:37], off
	s_nop 1
	v_mov_b64_e32 v[34:35], v[184:185]
	v_mov_b64_e32 v[36:37], v[186:187]
	s_nop 0
	s_nop 1
	v_mov_b64_e32 v[46:47], v[216:217]
	v_mov_b64_e32 v[48:49], v[218:219]
	s_waitcnt vmcnt(0)
	v_pk_fma_f32 v[30:31], v[34:35], v[30:31], v[46:47]
	v_pk_fma_f32 v[32:33], v[36:37], v[32:33], v[48:49]
	global_store_dwordx4 v[50:51], v[30:33], off offset:1024
	s_nop 1
	v_mov_b64_e32 v[30:31], v[188:189]
	v_mov_b64_e32 v[32:33], v[190:191]
	s_nop 1
	v_mov_b64_e32 v[34:35], v[220:221]
	v_mov_b64_e32 v[36:37], v[222:223]
	s_waitcnt vmcnt(0)
	v_pk_fma_f32 v[30:31], v[30:31], v[4:5], v[34:35]
	v_pk_fma_f32 v[32:33], v[32:33], v[38:39], v[36:37]
	global_store_dwordx4 v[50:51], v[30:33], off offset:2048
	s_nop 1
	v_mov_b64_e32 v[30:31], v[192:193]
	v_mov_b64_e32 v[32:33], v[194:195]
	s_nop 0
	s_nop 1
	v_mov_b64_e32 v[34:35], v[236:237]
	v_mov_b64_e32 v[36:37], v[238:239]
	v_pk_mul_f32 v[4:5], v[28:29], v[12:13] op_sel_hi:[1,0]
	s_waitcnt vmcnt(0)
	v_pk_fma_f32 v[26:27], v[30:31], v[26:27], v[34:35]
	v_add_co_u32_e32 v34, vcc, s82, v44
	v_pk_fma_f32 v[28:29], v[32:33], v[4:5], v[36:37]
	s_nop 0
	v_addc_co_u32_e32 v35, vcc, 0, v45, vcc
	global_store_dwordx4 v[50:51], v[26:29], off offset:3072
	v_add_co_u32_e32 v36, vcc, s82, v42
	s_nop 1
	v_mov_b64_e32 v[26:27], v[196:197]
	v_mov_b64_e32 v[28:29], v[198:199]
	s_nop 0
	v_addc_co_u32_e32 v37, vcc, 0, v43, vcc
	s_nop 1
	v_mov_b64_e32 v[30:31], v[240:241]
	v_mov_b64_e32 v[32:33], v[242:243]
	v_pk_mul_f32 v[4:5], v[22:23], v[12:13] op_sel_hi:[1,0]
	s_waitcnt vmcnt(0)
	v_pk_fma_f32 v[18:19], v[26:27], v[18:19], v[30:31]
	v_add_co_u32_e32 v26, vcc, s82, v50
	v_pk_fma_f32 v[20:21], v[28:29], v[4:5], v[32:33]
	s_nop 0
	v_addc_co_u32_e32 v27, vcc, 0, v51, vcc
	global_store_dwordx4 v[26:27], v[18:21], off
	s_nop 1
	v_mov_b64_e32 v[18:19], v[200:201]
	v_mov_b64_e32 v[20:21], v[202:203]
	s_nop 0
	s_nop 1
	v_mov_b64_e32 v[22:23], v[128:129]
	v_mov_b64_e32 v[24:25], v[130:131]
	v_pk_mul_f32 v[4:5], v[40:41], v[12:13] op_sel_hi:[1,0]
	s_waitcnt vmcnt(0)
	v_pk_fma_f32 v[2:3], v[18:19], v[2:3], v[22:23]
	v_pk_fma_f32 v[4:5], v[20:21], v[4:5], v[24:25]
	global_store_dwordx4 v[26:27], v[2:5], off offset:1024
	s_nop 1
	v_mov_b64_e32 v[2:3], v[204:205]
	v_mov_b64_e32 v[4:5], v[206:207]
	s_nop 1
	v_mov_b64_e32 v[18:19], v[132:133]
	v_mov_b64_e32 v[20:21], v[134:135]
	s_waitcnt vmcnt(0)
	v_pk_fma_f32 v[2:3], v[2:3], v[14:15], v[18:19]
	v_pk_fma_f32 v[4:5], v[4:5], v[16:17], v[20:21]
	global_store_dwordx4 v[26:27], v[2:5], off offset:2048
	s_nop 1
	v_mov_b64_e32 v[2:3], v[208:209]
	v_mov_b64_e32 v[4:5], v[210:211]
	s_nop 0
	s_nop 1
	v_mov_b64_e32 v[14:15], v[140:141]
	v_mov_b64_e32 v[16:17], v[142:143]
	s_waitcnt vmcnt(0)
	v_pk_fma_f32 v[2:3], v[8:9], v[2:3], v[14:15]
	v_pk_fma_f32 v[4:5], v[10:11], v[4:5], v[16:17]
	global_store_dwordx4 v[26:27], v[2:5], off offset:3072
	s_cbranch_scc1 .LBB0_1705

.LBB0_1728:
	s_or_b64 exec, exec, s[10:11]
	v_readlane_b32 s8, v254, 45
	v_readlane_b32 s9, v254, 46
	v_readlane_b32 s22, v254, 32
	v_readlane_b32 s24, v254, 14
	v_readlane_b32 s28, v254, 22
	s_and_b64 vcc, exec, s[8:9]
	v_readlane_b32 s23, v254, 33
	v_readlane_b32 s25, v254, 15
	v_readlane_b32 s29, v254, 23
	v_readlane_b32 s30, v254, 20
	s_waitcnt lgkmcnt(0)
	s_barrier
	v_readlane_b32 s31, v254, 21
	s_load_dwordx4 s[76:79], s[0:1], 0xb0
	v_lshlrev_b32_e32 v144, 4, v232
	v_add_u32_e32 v145, 0x1000, v144
	s_waitcnt lgkmcnt(0)
	global_load_dwordx4 v[180:183], v144, s[76:77]
	global_load_dwordx4 v[212:215], v144, s[78:79]
	global_load_dwordx4 v[184:187], v144, s[76:77] offset:1024
	global_load_dwordx4 v[216:219], v144, s[78:79] offset:1024
	global_load_dwordx4 v[188:191], v144, s[76:77] offset:2048
	global_load_dwordx4 v[220:223], v144, s[78:79] offset:2048
	global_load_dwordx4 v[192:195], v144, s[76:77] offset:3072
	global_load_dwordx4 v[236:239], v144, s[78:79] offset:3072
	global_load_dwordx4 v[196:199], v145, s[76:77]
	global_load_dwordx4 v[240:243], v145, s[78:79]
	global_load_dwordx4 v[200:203], v145, s[76:77] offset:1024
	global_load_dwordx4 v[128:131], v145, s[78:79] offset:1024
	global_load_dwordx4 v[204:207], v145, s[76:77] offset:2048
	global_load_dwordx4 v[132:135], v145, s[78:79] offset:2048
	global_load_dwordx4 v[208:211], v145, s[76:77] offset:3072
	global_load_dwordx4 v[140:143], v145, s[78:79] offset:3072
	s_cbranch_vccz .LBB0_1743

.LBB0_1743:
	v_mov_b32_e32 v2, v0
	s_mov_b64 s[8:9], s[44:45]
	v_mov_b32_e32 v1, v232
	s_mov_b64 s[34:35], s[46:47]
	s_mov_b64 s[10:11], s[0:1]
	s_add_i32 s8, s60, s30
	v_lshlrev_b32_e32 v2, 2, v1
	s_waitcnt lgkmcnt(0)
	v_ashrrev_i32_e32 v3, 31, v2
	v_lshlrev_b64 v[4:5], 1, v[2:3]
	v_lshl_add_u64 v[6:7], s[34:35], 0, v[4:5]
	v_lshl_add_u64 v[32:33], v[6:7], 0, s[24:25]
	global_load_dwordx2 v[6:7], v[32:33], off offset:-3584
	global_load_dwordx2 v[34:35], v[32:33], off offset:-3072
	global_load_dwordx2 v[44:45], v[32:33], off offset:-2560
	global_load_dwordx2 v[8:9], v[32:33], off offset:-2048
	s_cmpk_lt_i32 s8, 0x2000
	s_cselect_b32 s36, s8, s30
	s_add_u32 s18, s34, 0x28c000
	s_addc_u32 s19, s35, 0
	s_ashr_i32 s37, s36, 31
	s_ashr_i32 s31, s30, 31
	s_lshl_b64 s[8:9], s[36:37], 12
	s_add_u32 s16, s34, s8
	s_addc_u32 s17, s35, s9
	v_lshl_add_u64 v[4:5], s[16:17], 0, v[4:5]
	s_mov_b64 s[8:9], 0x1d91e000
	v_lshl_add_u64 v[224:225], v[4:5], 0, s[8:9]
	global_load_dwordx2 v[118:119], v[224:225], off
	global_load_dwordx2 v[120:121], v[224:225], off offset:512
	global_load_dwordx2 v[122:123], v[224:225], off offset:1024
	global_load_dwordx2 v[144:145], v[224:225], off offset:1536
	global_load_dwordx2 v[146:147], v[224:225], off offset:2048
	global_load_dwordx2 v[152:153], v[224:225], off offset:2560
	global_load_dwordx2 v[154:155], v[224:225], off offset:3072
	global_load_dwordx2 v[234:235], v[224:225], off offset:3584
	v_and_b32_e32 v14, 64, v249
	v_add_u32_e32 v14, 64, v14
	v_xor_b32_e32 v20, 1, v249
	v_lshlrev_b64 v[86:87], 2, v[2:3]
	s_add_u32 s20, s34, 0x28e000
	s_addc_u32 s21, s35, 0
	v_lshl_add_u64 v[88:89], s[20:21], 0, v[86:87]
	s_add_u32 s58, s34, 0x1515b000
	s_addc_u32 s59, s35, 0
	s_waitcnt vmcnt(3)
	v_lshlrev_b32_e32 v68, 16, v6
	s_waitcnt vmcnt(2)
	v_lshlrev_b32_e32 v69, 16, v34
	v_and_b32_e32 v75, 0xffff0000, v34
	s_waitcnt vmcnt(0)
	v_lshlrev_b32_e32 v36, 16, v8
	v_and_b32_e32 v37, 0xffff0000, v8
	v_lshlrev_b32_e32 v38, 16, v9
	v_and_b32_e32 v39, 0xffff0000, v9
	global_load_dwordx2 v[8:9], v[32:33], off offset:-1536
	v_and_b32_e32 v74, 0xffff0000, v6
	v_and_b32_e32 v73, 0xffff0000, v35
	v_and_b32_e32 v72, 0xffff0000, v7
	v_lshlrev_b32_e32 v34, 16, v44
	v_add_f32_e32 v66, v36, v37
	v_add_f32_e32 v46, v38, v39
	s_waitcnt vmcnt(0)
	v_lshlrev_b32_e32 v43, 16, v8
	v_and_b32_e32 v41, 0xffff0000, v8
	v_lshlrev_b32_e32 v67, 16, v9
	v_and_b32_e32 v47, 0xffff0000, v9
	global_load_dwordx2 v[70:71], v[32:33], off offset:-1024
	global_load_dwordx2 v[8:9], v[32:33], off offset:-512
	s_waitcnt vmcnt(0)
	v_lshlrev_b32_e32 v48, 16, v8
	v_and_b32_e32 v49, 0xffff0000, v8
	v_lshlrev_b32_e32 v50, 16, v9
	v_and_b32_e32 v51, 0xffff0000, v9
	global_load_dwordx2 v[8:9], v[32:33], off
	v_add_f32_e32 v64, v48, v49
	v_add_f32_e32 v54, v50, v51
	s_waitcnt vmcnt(0)
	v_lshlrev_b32_e32 v52, 16, v8
	v_and_b32_e32 v53, 0xffff0000, v8
	v_lshlrev_b32_e32 v65, 16, v9
	v_and_b32_e32 v55, 0xffff0000, v9
	v_lshl_add_u64 v[8:9], v[4:5], 0, s[8:9]
	s_mov_b32 s8, 0x1d91e000
	v_add_co_u32_e32 v4, vcc, s8, v4
	s_nop 1
	v_addc_co_u32_e32 v5, vcc, 0, v5, vcc
	s_nop 1
	v_mov_b64_e32 v[60:61], v[118:119]
	s_nop 1
	v_mov_b64_e32 v[62:63], v[120:121]
	s_nop 1
	v_mov_b64_e32 v[58:59], v[122:123]
	s_nop 0
	s_nop 1
	v_mov_b64_e32 v[4:5], v[144:145]
	v_cmp_lt_i32_e32 vcc, v20, v14
	s_waitcnt vmcnt(0)
	v_lshlrev_b32_e32 v28, 16, v4
	v_and_b32_e32 v29, 0xffff0000, v4
	v_lshlrev_b32_e32 v30, 16, v5
	v_and_b32_e32 v31, 0xffff0000, v5
	s_nop 1
	v_mov_b64_e32 v[4:5], v[146:147]
	v_cndmask_b32_e32 v20, v249, v20, vcc
	v_lshlrev_b32_e32 v90, 2, v20
	v_add_f32_e32 v26, v28, v29
	v_add_f32_e32 v24, v30, v31
	s_waitcnt vmcnt(0)
	v_lshlrev_b32_e32 v23, 16, v4
	v_and_b32_e32 v21, 0xffff0000, v4
	v_lshlrev_b32_e32 v27, 16, v5
	v_and_b32_e32 v25, 0xffff0000, v5
	s_nop 1
	v_mov_b64_e32 v[56:57], v[152:153]
	s_nop 1
	v_mov_b64_e32 v[4:5], v[154:155]
	s_load_dwordx4 s[12:15], s[10:11], 0xb0
	s_load_dwordx2 s[38:39], s[10:11], 0x68
	s_waitcnt lgkmcnt(0)
	v_lshl_add_u64 v[84:85], s[12:13], 0, v[86:87]
	s_waitcnt vmcnt(0)
	v_lshlrev_b32_e32 v16, 16, v4
	v_and_b32_e32 v17, 0xffff0000, v4
	v_lshlrev_b32_e32 v18, 16, v5
	v_and_b32_e32 v19, 0xffff0000, v5
	s_nop 1
	v_mov_b64_e32 v[4:5], v[234:235]
	v_lshlrev_b32_e32 v9, 16, v35
	v_lshlrev_b32_e32 v8, 16, v7
	v_pk_add_f32 v[6:7], v[8:9], v[72:73]
	v_lshlrev_b32_e32 v35, 16, v45
	s_waitcnt vmcnt(0)
	v_lshlrev_b32_e32 v10, 16, v4
	v_and_b32_e32 v11, 0xffff0000, v4
	v_lshlrev_b32_e32 v15, 16, v5
	v_and_b32_e32 v13, 0xffff0000, v5
	v_pk_add_f32 v[4:5], v[68:69], v[74:75]
	s_nop 0
	v_pk_add_f32 v[4:5], v[4:5], v[6:7]
	v_and_b32_e32 v7, 0xffff0000, v45
	v_add_f32_e32 v4, 0, v4
	v_and_b32_e32 v6, 0xffff0000, v44
	v_add_f32_e32 v42, v4, v5
	v_pk_add_f32 v[4:5], v[34:35], v[6:7]
	v_pk_add_f32 v[44:45], v[66:67], v[46:47]
	v_pk_add_f32 v[4:5], v[4:5], v[4:5] op_sel:[0,1] op_sel_hi:[1,0]
	s_nop 0
	v_mov_b32_e32 v5, v41
	v_pk_add_f32 v[4:5], v[42:43], v[4:5]
	s_nop 0
	v_pk_add_f32 v[76:77], v[4:5], v[44:45]
	v_lshlrev_b32_e32 v45, 16, v71
	v_lshlrev_b32_e32 v44, 16, v70
	v_and_b32_e32 v5, 0xffff0000, v71
	v_and_b32_e32 v4, 0xffff0000, v70
	v_pk_add_f32 v[70:71], v[44:45], v[4:5]
	v_pk_add_f32 v[76:77], v[76:77], v[76:77] op_sel:[0,1] op_sel_hi:[1,0]
	v_pk_add_f32 v[70:71], v[70:71], v[70:71] op_sel:[0,1] op_sel_hi:[1,0]
	v_mov_b32_e32 v77, v52
	v_mov_b32_e32 v71, v53
	v_pk_add_f32 v[70:71], v[76:77], v[70:71]
	v_pk_add_f32 v[76:77], v[64:65], v[54:55]
	s_nop 0
	v_pk_add_f32 v[70:71], v[70:71], v[76:77]
	s_nop 0
	v_add_f32_e32 v12, v70, v71
	ds_bpermute_b32 v20, v90, v12
	s_waitcnt lgkmcnt(0)
	v_add_f32_e32 v12, v12, v20
	v_xor_b32_e32 v20, 2, v249
	v_cmp_lt_i32_e32 vcc, v20, v14
	s_nop 1
	v_cndmask_b32_e32 v20, v249, v20, vcc
	v_lshlrev_b32_e32 v91, 2, v20
	ds_bpermute_b32 v20, v91, v12
	s_waitcnt lgkmcnt(0)
	v_add_f32_e32 v12, v12, v20
	v_xor_b32_e32 v20, 4, v249
	v_cmp_lt_i32_e32 vcc, v20, v14
	s_nop 1
	v_cndmask_b32_e32 v20, v249, v20, vcc
	v_lshlrev_b32_e32 v92, 2, v20
	ds_bpermute_b32 v20, v92, v12
	s_waitcnt lgkmcnt(0)
	v_add_f32_e32 v12, v12, v20
	v_xor_b32_e32 v20, 8, v249
	v_cmp_lt_i32_e32 vcc, v20, v14
	s_nop 1
	v_cndmask_b32_e32 v20, v249, v20, vcc
	v_lshlrev_b32_e32 v93, 2, v20
	ds_bpermute_b32 v20, v93, v12
	s_waitcnt lgkmcnt(0)
	v_add_f32_e32 v12, v12, v20
	v_xor_b32_e32 v20, 16, v249
	v_cmp_lt_i32_e32 vcc, v20, v14
	s_nop 1
	v_cndmask_b32_e32 v20, v249, v20, vcc
	v_lshlrev_b32_e32 v94, 2, v20
	ds_bpermute_b32 v20, v94, v12
	s_waitcnt lgkmcnt(0)
	v_add_f32_e32 v12, v12, v20
	v_xor_b32_e32 v20, 32, v249
	v_cmp_lt_i32_e32 vcc, v20, v14
	s_nop 1
	v_cndmask_b32_e32 v14, v249, v20, vcc
	v_lshlrev_b32_e32 v95, 2, v14
	ds_bpermute_b32 v14, v95, v12
	s_waitcnt lgkmcnt(0)
	v_add_f32_e32 v12, v12, v14
	v_fmac_f32_e32 v74, 0xba000000, v12
	v_fmac_f32_e32 v75, 0xba000000, v12
	v_fmac_f32_e32 v72, 0xba000000, v12
	v_fmac_f32_e32 v68, 0xba000000, v12
	v_fmac_f32_e32 v73, 0xba000000, v12
	v_fmac_f32_e32 v69, 0xba000000, v12
	v_mov_b32_e32 v71, v75
	v_mov_b32_e32 v77, v74
	v_pk_mul_f32 v[74:75], v[74:75], v[74:75]
	v_fmac_f32_e32 v8, 0xba000000, v12
	v_fmac_f32_e32 v9, 0xba000000, v12
	v_mov_b32_e32 v70, v69
	v_mov_b32_e32 v76, v68
	v_pk_fma_f32 v[68:69], v[68:69], v[68:69], v[74:75]
	v_mov_b32_e32 v75, v73
	v_mov_b32_e32 v79, v72
	v_pk_mul_f32 v[72:73], v[72:73], v[72:73]
	v_fmac_f32_e32 v6, 0xba000000, v12
	v_fmac_f32_e32 v7, 0xba000000, v12
	v_fmac_f32_e32 v35, 0xba000000, v12
	v_mov_b32_e32 v74, v9
	v_mov_b32_e32 v78, v8
	v_pk_fma_f32 v[8:9], v[8:9], v[8:9], v[72:73]
	v_fmac_f32_e32 v34, 0xba000000, v12
	v_mov_b32_e32 v72, v35
	v_mov_b32_e32 v73, v7
	v_mov_b32_e32 v35, v6
	v_pk_add_f32 v[8:9], v[68:69], v[8:9]
	v_pk_mul_f32 v[68:69], v[72:73], v[72:73]
	v_pk_mul_f32 v[6:7], v[34:35], v[34:35]
	v_fmac_f32_e32 v36, 0xba000000, v12
	v_pk_mov_b32 v[80:81], v[6:7], v[68:69] op_sel:[1,0]
	v_mov_b32_e32 v7, v69
	v_pk_add_f32 v[6:7], v[80:81], v[6:7]
	v_fmac_f32_e32 v37, 0xba000000, v12
	v_pk_add_f32 v[6:7], v[6:7], v[6:7] op_sel_hi:[0,1]
	v_fmac_f32_e32 v38, 0xba000000, v12
	v_mul_f32_e32 v6, v36, v36
	v_fmac_f32_e32 v39, 0xba000000, v12
	v_pk_fma_f32 v[68:69], v[36:37], v[36:37], v[6:7] op_sel_hi:[1,1,0]
	v_mul_f32_e32 v6, v38, v38
	v_pk_add_f32 v[8:9], v[8:9], v[8:9] op_sel_hi:[0,1]
	v_pk_fma_f32 v[80:81], v[38:39], v[38:39], v[6:7] op_sel_hi:[1,1,0]
	v_fmac_f32_e32 v47, 0xba000000, v12
	v_fmac_f32_e32 v67, 0xba000000, v12
	v_fmac_f32_e32 v41, 0xba000000, v12
	v_fmac_f32_e32 v43, 0xba000000, v12
	v_mul_f32_e32 v68, v43, v43
	v_mul_f32_e32 v80, v41, v41
	v_mul_f32_e32 v6, v67, v67
	v_mul_f32_e32 v8, v47, v47
	v_pk_add_f32 v[68:69], v[68:69], v[80:81]
	v_pk_add_f32 v[6:7], v[6:7], v[8:9]
	v_fmac_f32_e32 v4, 0xba000000, v12
	v_fmac_f32_e32 v5, 0xba000000, v12
	v_fmac_f32_e32 v45, 0xba000000, v12
	v_pk_add_f32 v[6:7], v[68:69], v[6:7]
	v_fmac_f32_e32 v44, 0xba000000, v12
	v_mov_b32_e32 v68, v45
	v_mov_b32_e32 v69, v5
	v_mov_b32_e32 v45, v4
	v_pk_mul_f32 v[8:9], v[68:69], v[68:69]
	v_pk_mul_f32 v[4:5], v[44:45], v[44:45]
	v_fmac_f32_e32 v48, 0xba000000, v12
	v_pk_mov_b32 v[80:81], v[4:5], v[8:9] op_sel:[1,0]
	v_mov_b32_e32 v5, v9
	v_pk_add_f32 v[4:5], v[80:81], v[4:5]
	v_fmac_f32_e32 v49, 0xba000000, v12
	v_pk_add_f32 v[4:5], v[4:5], v[4:5] op_sel_hi:[0,1]
	v_fmac_f32_e32 v50, 0xba000000, v12
	v_mul_f32_e32 v4, v48, v48
	v_fmac_f32_e32 v51, 0xba000000, v12
	v_pk_fma_f32 v[8:9], v[48:49], v[48:49], v[4:5] op_sel_hi:[1,1,0]
	v_mul_f32_e32 v4, v50, v50
	v_pk_add_f32 v[6:7], v[6:7], v[6:7] op_sel_hi:[0,1]
	v_pk_fma_f32 v[80:81], v[50:51], v[50:51], v[4:5] op_sel_hi:[1,1,0]
	v_fmac_f32_e32 v55, 0xba000000, v12
	v_fmac_f32_e32 v65, 0xba000000, v12
	v_fmac_f32_e32 v53, 0xba000000, v12
	v_fmac_f32_e32 v52, 0xba000000, v12
	v_mul_f32_e32 v8, v52, v52
	v_mul_f32_e32 v80, v53, v53
	v_mul_f32_e32 v4, v65, v65
	v_mul_f32_e32 v6, v55, v55
	v_pk_add_f32 v[8:9], v[8:9], v[80:81]
	v_pk_add_f32 v[4:5], v[4:5], v[6:7]
	v_lshl_add_u64 v[80:81], s[14:15], 0, v[86:87]
	v_pk_add_f32 v[4:5], v[8:9], v[4:5]
	v_mov_b32_e32 v46, v67
	v_add_f32_e32 v4, v4, v5
	ds_bpermute_b32 v5, v90, v4
	v_mov_b32_e32 v40, v43
	v_mov_b32_e32 v54, v65
	s_waitcnt lgkmcnt(0)
	v_add_f32_e32 v4, v4, v5
	ds_bpermute_b32 v5, v91, v4
	s_waitcnt lgkmcnt(0)
	v_add_f32_e32 v4, v4, v5
	ds_bpermute_b32 v5, v92, v4
	s_waitcnt lgkmcnt(0)
	v_add_f32_e32 v4, v4, v5
	ds_bpermute_b32 v5, v93, v4
	s_waitcnt lgkmcnt(0)
	v_add_f32_e32 v4, v4, v5
	ds_bpermute_b32 v5, v94, v4
	s_waitcnt lgkmcnt(0)
	v_add_f32_e32 v4, v4, v5
	ds_bpermute_b32 v5, v95, v4
	s_waitcnt lgkmcnt(0)
	v_add_f32_e32 v4, v4, v5
	v_fmamk_f32 v4, v4, 0x3a000000, v250
	v_cmp_gt_f32_e32 vcc, s96, v4
	v_mul_f32_e32 v5, 0x4f800000, v4
	s_nop 0
	v_cndmask_b32_e32 v4, v4, v5, vcc
	v_sqrt_f32_e32 v5, v4
	s_nop 0
	v_add_u32_e32 v6, -1, v5
	v_fma_f32 v7, -v6, v5, v4
	v_cmp_ge_f32_e64 s[10:11], 0, v7
	v_add_u32_e32 v7, 1, v5
	s_nop 0
	v_cndmask_b32_e64 v6, v5, v6, s[10:11]
	v_fma_f32 v5, -v7, v5, v4
	v_cmp_lt_f32_e64 s[10:11], 0, v5
	s_nop 1
	v_cndmask_b32_e64 v5, v6, v7, s[10:11]
	v_mul_f32_e32 v6, 0x37800000, v5
	v_cndmask_b32_e32 v5, v5, v6, vcc
	v_cmp_class_f32_e32 vcc, v4, v251
	s_nop 1
	v_cndmask_b32_e32 v4, v5, v4, vcc
	v_div_scale_f32 v5, s[8:9], v4, v4, 1.0
	v_rcp_f32_e32 v6, v5
	s_movk_i32 s8, 0xf000
	v_fma_f32 v7, -v5, v6, 1.0
	v_fmac_f32_e32 v6, v7, v6
	v_div_scale_f32 v7, vcc, 1.0, v4, 1.0
	v_mul_f32_e32 v8, v7, v6
	v_fma_f32 v9, -v5, v8, v7
	v_fmac_f32_e32 v8, v9, v6
	v_fma_f32 v5, -v5, v8, v7
	v_div_fmas_f32 v5, v5, v6, v8
	v_div_fixup_f32 v12, v5, v4, 1.0
	s_nop 1
	v_mov_b64_e32 v[2:3], v[180:181]
	v_mov_b64_e32 v[4:5], v[182:183]
	s_nop 1
	v_mov_b64_e32 v[6:7], v[212:213]
	v_mov_b64_e32 v[8:9], v[214:215]
	v_pk_mul_f32 v[76:77], v[76:77], v[12:13] op_sel_hi:[1,0]
	v_pk_mul_f32 v[78:79], v[78:79], v[12:13] op_sel_hi:[1,0]
	v_pk_mul_f32 v[70:71], v[70:71], v[12:13] op_sel_hi:[1,0]
	v_pk_mul_f32 v[34:35], v[34:35], v[12:13] op_sel_hi:[1,0]
	v_pk_mul_f32 v[38:39], v[38:39], v[12:13] op_sel_hi:[1,0]
	v_pk_mul_f32 v[36:37], v[36:37], v[12:13] op_sel_hi:[1,0]
	v_pk_mul_f32 v[46:47], v[46:47], v[12:13] op_sel_hi:[1,0]
	v_pk_mul_f32 v[40:41], v[40:41], v[12:13] op_sel_hi:[1,0]
	v_pk_mul_f32 v[44:45], v[44:45], v[12:13] op_sel_hi:[1,0]
	v_pk_mul_f32 v[50:51], v[50:51], v[12:13] op_sel_hi:[1,0]
	v_pk_mul_f32 v[48:49], v[48:49], v[12:13] op_sel_hi:[1,0]
	v_pk_mul_f32 v[54:55], v[54:55], v[12:13] op_sel_hi:[1,0]
	v_pk_mul_f32 v[52:53], v[52:53], v[12:13] op_sel_hi:[1,0]
	s_waitcnt vmcnt(0)
	v_pk_fma_f32 v[6:7], v[2:3], v[76:77], v[6:7]
	v_lshl_add_u64 v[2:3], s[34:35], 0, v[86:87]
	v_lshl_add_u64 v[76:77], v[2:3], 0, s[22:23]
	v_add_co_u32_e32 v104, vcc, s8, v76
	v_pk_fma_f32 v[8:9], v[4:5], v[78:79], v[8:9]
	s_nop 0
	v_addc_co_u32_e32 v105, vcc, -1, v77, vcc
	global_store_dwordx4 v[104:105], v[6:9], off offset:-3072
	global_load_dwordx4 v[2:5], v[88:89], off
	v_lshl_add_u64 v[86:87], s[18:19], 0, v[86:87]
	global_load_dwordx4 v[96:99], v[86:87], off
	s_mov_b32 s8, 0xef2fd000
	s_waitcnt vmcnt(1)
	v_pk_add_f32 v[4:5], v[4:5], 1.0 op_sel_hi:[1,0]
	v_pk_add_f32 v[78:79], v[2:3], 1.0 op_sel_hi:[1,0]
	s_waitcnt vmcnt(0)
	v_pk_fma_f32 v[2:3], v[4:5], v[8:9], v[98:99]
	v_pk_fma_f32 v[4:5], v[78:79], v[6:7], v[96:97]
	s_nop 0
	s_nop 0
	s_nop 0
	s_nop 0
	s_nop 0
	s_nop 0
	v_cvt_pk_bf16_f32 v6, v4, v5
	s_nop 0
	s_nop 0
	s_nop 0
	s_nop 0
	v_add_co_u32_e32 v78, vcc, s8, v32
	v_cvt_pk_bf16_f32 v7, v2, v3
	s_nop 0
	v_addc_co_u32_e32 v79, vcc, -1, v33, vcc
	global_store_dwordx2 v[78:79], v[6:7], off offset:-3584
	s_nop 1
	v_mov_b64_e32 v[6:7], v[184:185]
	v_mov_b64_e32 v[8:9], v[186:187]
	s_nop 0
	s_nop 1
	v_mov_b64_e32 v[96:97], v[216:217]
	v_mov_b64_e32 v[98:99], v[218:219]
	v_pk_mul_f32 v[32:33], v[74:75], v[12:13] op_sel_hi:[1,0]
	s_lshl_b64 s[8:9], s[36:37], 13
	s_add_u32 s40, s34, s8
	s_addc_u32 s41, s35, s9
	s_waitcnt vmcnt(0)
	v_pk_fma_f32 v[96:97], v[6:7], v[70:71], v[96:97]
	v_pk_fma_f32 v[98:99], v[8:9], v[32:33], v[98:99]
	global_store_dwordx4 v[104:105], v[96:99], off offset:-2048
	global_load_dwordx4 v[6:9], v[88:89], off offset:1024
	global_load_dwordx4 v[100:103], v[86:87], off offset:1024
	s_waitcnt vmcnt(1)
	v_pk_add_f32 v[8:9], v[8:9], 1.0 op_sel_hi:[1,0]
	v_pk_add_f32 v[32:33], v[6:7], 1.0 op_sel_hi:[1,0]
	s_waitcnt vmcnt(0)
	v_pk_fma_f32 v[6:7], v[8:9], v[98:99], v[102:103]
	v_pk_fma_f32 v[8:9], v[32:33], v[96:97], v[100:101]
	s_nop 0
	s_nop 0
	s_nop 0
	s_nop 0
	s_nop 0
	s_nop 0
	v_cvt_pk_bf16_f32 v32, v8, v9
	s_nop 0
	s_nop 0
	s_nop 0
	s_nop 0
	s_nop 0
	v_cvt_pk_bf16_f32 v33, v6, v7
	global_store_dwordx2 v[78:79], v[32:33], off offset:-3072
	s_nop 1
	v_mov_b64_e32 v[96:97], v[188:189]
	v_mov_b64_e32 v[98:99], v[190:191]
	s_nop 1
	v_mov_b64_e32 v[100:101], v[220:221]
	v_mov_b64_e32 v[102:103], v[222:223]
	v_pk_mul_f32 v[32:33], v[72:73], v[12:13] op_sel_hi:[1,0]
	s_waitcnt vmcnt(0)
	v_pk_fma_f32 v[70:71], v[96:97], v[34:35], v[100:101]
	v_pk_fma_f32 v[72:73], v[98:99], v[32:33], v[102:103]
	global_store_dwordx4 v[104:105], v[70:73], off offset:-1024
	global_load_dwordx4 v[32:35], v[88:89], off offset:2048
	global_load_dwordx4 v[96:99], v[86:87], off offset:2048
	s_waitcnt vmcnt(1)
	v_pk_add_f32 v[34:35], v[34:35], 1.0 op_sel_hi:[1,0]
	v_pk_add_f32 v[74:75], v[32:33], 1.0 op_sel_hi:[1,0]
	s_waitcnt vmcnt(0)
	v_pk_fma_f32 v[32:33], v[34:35], v[72:73], v[98:99]
	v_pk_fma_f32 v[34:35], v[74:75], v[70:71], v[96:97]
	s_nop 0
	s_nop 0
	s_nop 0
	s_nop 0
	s_nop 0
	s_nop 0
	v_cvt_pk_bf16_f32 v70, v34, v35
	s_nop 0
	s_nop 0
	s_nop 0
	s_nop 0
	s_nop 0
	v_cvt_pk_bf16_f32 v71, v32, v33
	global_store_dwordx2 v[78:79], v[70:71], off offset:-2560
	s_nop 1
	v_mov_b64_e32 v[70:71], v[192:193]
	v_mov_b64_e32 v[72:73], v[194:195]
	s_nop 0
	s_nop 1
	v_mov_b64_e32 v[96:97], v[236:237]
	v_mov_b64_e32 v[98:99], v[238:239]
	s_waitcnt vmcnt(0)
	v_pk_fma_f32 v[70:71], v[70:71], v[36:37], v[96:97]
	v_pk_fma_f32 v[72:73], v[72:73], v[38:39], v[98:99]
	global_store_dwordx4 v[76:77], v[70:73], off offset:-4096
	global_load_dwordx4 v[36:39], v[88:89], off offset:3072
	global_load_dwordx4 v[96:99], v[86:87], off offset:3072
	s_waitcnt vmcnt(1)
	v_pk_add_f32 v[38:39], v[38:39], 1.0 op_sel_hi:[1,0]
	v_pk_add_f32 v[74:75], v[36:37], 1.0 op_sel_hi:[1,0]
	s_waitcnt vmcnt(0)
	v_pk_fma_f32 v[36:37], v[38:39], v[72:73], v[98:99]
	v_pk_fma_f32 v[38:39], v[74:75], v[70:71], v[96:97]
	s_nop 0
	s_nop 0
	s_nop 0
	s_nop 0
	s_nop 0
	s_nop 0
	v_cvt_pk_bf16_f32 v70, v38, v39
	s_nop 0
	s_nop 0
	s_nop 0
	s_nop 0
	s_nop 0
	v_cvt_pk_bf16_f32 v71, v36, v37
	global_store_dwordx2 v[78:79], v[70:71], off offset:-2048
	v_add_co_u32_e32 v70, vcc, s82, v84
	s_nop 1
	v_addc_co_u32_e32 v71, vcc, 0, v85, vcc
	v_add_co_u32_e32 v72, vcc, s82, v80
	s_nop 1
	v_mov_b64_e32 v[96:97], v[196:197]
	v_mov_b64_e32 v[98:99], v[198:199]
	s_nop 0
	v_addc_co_u32_e32 v73, vcc, 0, v81, vcc
	s_nop 1
	v_mov_b64_e32 v[100:101], v[240:241]
	v_mov_b64_e32 v[102:103], v[242:243]
	v_add_co_u32_e32 v66, vcc, s82, v88
	s_waitcnt vmcnt(0)
	v_pk_fma_f32 v[96:97], v[40:41], v[96:97], v[100:101]
	v_pk_fma_f32 v[98:99], v[46:47], v[98:99], v[102:103]
	v_addc_co_u32_e32 v67, vcc, 0, v89, vcc
	global_store_dwordx4 v[76:77], v[96:99], off offset:-3072
	v_add_co_u32_e32 v80, vcc, s82, v86
	global_load_dwordx4 v[40:43], v[66:67], off
	s_nop 0
	v_addc_co_u32_e32 v81, vcc, 0, v87, vcc
	global_load_dwordx4 v[84:87], v[80:81], off
	s_waitcnt vmcnt(1)
	v_pk_add_f32 v[42:43], v[42:43], 1.0 op_sel_hi:[1,0]
	v_pk_add_f32 v[46:47], v[40:41], 1.0 op_sel_hi:[1,0]
	s_waitcnt vmcnt(0)
	v_pk_fma_f32 v[40:41], v[98:99], v[42:43], v[86:87]
	v_pk_fma_f32 v[42:43], v[96:97], v[46:47], v[84:85]
	s_nop 0
	s_nop 0
	s_nop 0
	s_nop 0
	s_nop 0
	s_nop 0
	v_cvt_pk_bf16_f32 v46, v42, v43
	s_nop 0
	s_nop 0
	s_nop 0
	s_nop 0
	s_nop 0
	v_cvt_pk_bf16_f32 v47, v40, v41
	global_store_dwordx2 v[78:79], v[46:47], off offset:-1536
	s_nop 1
	v_mov_b64_e32 v[84:85], v[200:201]
	v_mov_b64_e32 v[86:87], v[202:203]
	s_nop 1
	v_mov_b64_e32 v[96:97], v[128:129]
	v_mov_b64_e32 v[98:99], v[130:131]
	v_pk_mul_f32 v[46:47], v[68:69], v[12:13] op_sel_hi:[1,0]
	s_waitcnt vmcnt(0)
	v_pk_fma_f32 v[84:85], v[44:45], v[84:85], v[96:97]
	v_pk_fma_f32 v[86:87], v[46:47], v[86:87], v[98:99]
	global_store_dwordx4 v[76:77], v[84:87], off offset:-2048
	global_load_dwordx4 v[44:47], v[66:67], off offset:1024
	global_load_dwordx4 v[96:99], v[80:81], off offset:1024
	s_waitcnt vmcnt(1)
	v_pk_add_f32 v[46:47], v[46:47], 1.0 op_sel_hi:[1,0]
	v_pk_add_f32 v[68:69], v[44:45], 1.0 op_sel_hi:[1,0]
	s_waitcnt vmcnt(0)
	v_pk_fma_f32 v[44:45], v[86:87], v[46:47], v[98:99]
	v_pk_fma_f32 v[46:47], v[84:85], v[68:69], v[96:97]
	s_nop 0
	s_nop 0
	s_nop 0
	s_nop 0
	s_nop 0
	s_nop 0
	v_cvt_pk_bf16_f32 v68, v46, v47
	s_nop 0
	s_nop 0
	s_nop 0
	s_nop 0
	s_nop 0
	v_cvt_pk_bf16_f32 v69, v44, v45
	global_store_dwordx2 v[78:79], v[68:69], off offset:-1024
	s_nop 1
	v_mov_b64_e32 v[84:85], v[204:205]
	v_mov_b64_e32 v[86:87], v[206:207]
	s_nop 1
	v_mov_b64_e32 v[96:97], v[132:133]
	v_mov_b64_e32 v[98:99], v[134:135]
	s_waitcnt vmcnt(0)
	v_pk_fma_f32 v[84:85], v[48:49], v[84:85], v[96:97]
	v_pk_fma_f32 v[86:87], v[50:51], v[86:87], v[98:99]
	global_store_dwordx4 v[76:77], v[84:87], off offset:-1024
	global_load_dwordx4 v[48:51], v[66:67], off offset:2048
	global_load_dwordx4 v[96:99], v[80:81], off offset:2048
	s_waitcnt vmcnt(1)
	v_pk_add_f32 v[50:51], v[50:51], 1.0 op_sel_hi:[1,0]
	v_pk_add_f32 v[68:69], v[48:49], 1.0 op_sel_hi:[1,0]
	s_waitcnt vmcnt(0)
	v_pk_fma_f32 v[48:49], v[86:87], v[50:51], v[98:99]
	v_pk_fma_f32 v[50:51], v[84:85], v[68:69], v[96:97]
	s_nop 0
	s_nop 0
	s_nop 0
	s_nop 0
	s_nop 0
	s_nop 0
	v_cvt_pk_bf16_f32 v68, v50, v51
	s_nop 0
	s_nop 0
	s_nop 0
	s_nop 0
	s_nop 0
	v_cvt_pk_bf16_f32 v69, v48, v49
	global_store_dwordx2 v[78:79], v[68:69], off offset:-512
	s_nop 1
	v_mov_b64_e32 v[68:69], v[208:209]
	v_mov_b64_e32 v[70:71], v[210:211]
	s_nop 0
	s_nop 1
	v_mov_b64_e32 v[72:73], v[140:141]
	v_mov_b64_e32 v[74:75], v[142:143]
	s_waitcnt vmcnt(0)
	v_pk_fma_f32 v[68:69], v[52:53], v[68:69], v[72:73]
	v_pk_fma_f32 v[70:71], v[54:55], v[70:71], v[74:75]
	global_store_dwordx4 v[76:77], v[68:71], off
	global_load_dwordx4 v[52:55], v[66:67], off offset:3072
	s_nop 0
	global_load_dwordx4 v[64:67], v[80:81], off offset:3072
	v_and_b32_e32 v77, 0xffff0000, v63
	v_and_b32_e32 v76, 0xffff0000, v61
	v_and_b32_e32 v75, 0xffff0000, v59
	v_and_b32_e32 v74, 0xffff0000, v58
	s_waitcnt vmcnt(1)
	v_pk_add_f32 v[54:55], v[54:55], 1.0 op_sel_hi:[1,0]
	v_pk_add_f32 v[72:73], v[52:53], 1.0 op_sel_hi:[1,0]
	s_waitcnt vmcnt(0)
	v_pk_fma_f32 v[52:53], v[70:71], v[54:55], v[66:67]
	v_pk_fma_f32 v[54:55], v[68:69], v[72:73], v[64:65]
	v_and_b32_e32 v67, 0xffff0000, v62
	v_cvt_pk_bf16_f32 v64, v54, v55
	v_cvt_pk_bf16_f32 v65, v52, v53
	global_store_dwordx2 v[78:79], v[64:65], off
	v_lshlrev_b32_e32 v64, 16, v60
	v_lshlrev_b32_e32 v65, 16, v62
	v_and_b32_e32 v66, 0xffff0000, v60
	v_lshlrev_b32_e32 v70, 16, v61
	v_lshlrev_b32_e32 v71, 16, v63
	v_pk_add_f32 v[60:61], v[64:65], v[66:67]
	v_pk_add_f32 v[62:63], v[70:71], v[76:77]
	v_lshlrev_b32_e32 v69, 16, v59
	v_lshlrev_b32_e32 v68, 16, v58
	v_pk_add_f32 v[60:61], v[60:61], v[62:63]
	v_pk_add_f32 v[58:59], v[68:69], v[74:75]
	v_add_f32_e32 v12, 0, v60
	v_pk_add_f32 v[58:59], v[58:59], v[58:59] op_sel:[0,1] op_sel_hi:[1,0]
	v_add_f32_e32 v22, v12, v61
	v_mov_b32_e32 v59, v21
	v_pk_add_f32 v[58:59], v[22:23], v[58:59]
	v_pk_add_f32 v[60:61], v[26:27], v[24:25]
	v_and_b32_e32 v73, 0xffff0000, v57
	v_pk_add_f32 v[58:59], v[58:59], v[60:61]
	v_lshlrev_b32_e32 v61, 16, v57
	v_lshlrev_b32_e32 v60, 16, v56
	v_and_b32_e32 v72, 0xffff0000, v56
	v_pk_add_f32 v[56:57], v[60:61], v[72:73]
	v_pk_add_f32 v[58:59], v[58:59], v[58:59] op_sel:[0,1] op_sel_hi:[1,0]
	v_pk_add_f32 v[56:57], v[56:57], v[56:57] op_sel:[0,1] op_sel_hi:[1,0]
	v_add_f32_e32 v14, v16, v17
	v_add_f32_e32 v12, v18, v19
	v_mov_b32_e32 v59, v10
	v_mov_b32_e32 v57, v11
	v_pk_add_f32 v[56:57], v[58:59], v[56:57]
	v_pk_add_f32 v[58:59], v[14:15], v[12:13]
	s_nop 0
	v_pk_add_f32 v[56:57], v[56:57], v[58:59]
	s_nop 0
	v_add_f32_e32 v12, v56, v57
	ds_bpermute_b32 v14, v90, v12
	s_waitcnt lgkmcnt(0)
	v_add_f32_e32 v12, v12, v14
	ds_bpermute_b32 v14, v91, v12
	s_waitcnt lgkmcnt(0)
	v_add_f32_e32 v12, v12, v14
	ds_bpermute_b32 v14, v92, v12
	s_waitcnt lgkmcnt(0)
	v_add_f32_e32 v12, v12, v14
	ds_bpermute_b32 v14, v93, v12
	s_waitcnt lgkmcnt(0)
	v_add_f32_e32 v12, v12, v14
	ds_bpermute_b32 v14, v94, v12
	s_waitcnt lgkmcnt(0)
	v_add_f32_e32 v12, v12, v14
	ds_bpermute_b32 v14, v95, v12
	s_waitcnt lgkmcnt(0)
	v_add_f32_e32 v14, v12, v14
	v_fmac_f32_e32 v66, 0xba000000, v14
	v_fmac_f32_e32 v67, 0xba000000, v14
	v_fmac_f32_e32 v76, 0xba000000, v14
	v_fmac_f32_e32 v64, 0xba000000, v14
	v_fmac_f32_e32 v77, 0xba000000, v14
	v_fmac_f32_e32 v65, 0xba000000, v14
	v_pk_mul_f32 v[58:59], v[66:67], v[66:67]
	v_fmac_f32_e32 v70, 0xba000000, v14
	v_fmac_f32_e32 v71, 0xba000000, v14
	v_mov_b32_e32 v62, v65
	v_mov_b32_e32 v63, v67
	v_mov_b32_e32 v56, v64
	v_pk_fma_f32 v[64:65], v[64:65], v[64:65], v[58:59]
	v_mov_b32_e32 v67, v77
	v_mov_b32_e32 v59, v76
	v_pk_mul_f32 v[76:77], v[76:77], v[76:77]
	v_mov_b32_e32 v57, v66
	v_mov_b32_e32 v66, v71
	v_mov_b32_e32 v58, v70
	v_pk_fma_f32 v[70:71], v[70:71], v[70:71], v[76:77]
	v_fmac_f32_e32 v74, 0xba000000, v14
	v_fmac_f32_e32 v75, 0xba000000, v14
	v_fmac_f32_e32 v69, 0xba000000, v14
	v_pk_add_f32 v[64:65], v[64:65], v[70:71]
	v_fmac_f32_e32 v68, 0xba000000, v14
	v_mov_b32_e32 v70, v69
	v_mov_b32_e32 v71, v75
	v_mov_b32_e32 v69, v74
	v_pk_mul_f32 v[76:77], v[70:71], v[70:71]
	v_pk_mul_f32 v[74:75], v[68:69], v[68:69]
	v_fmac_f32_e32 v28, 0xba000000, v14
	v_pk_mov_b32 v[78:79], v[74:75], v[76:77] op_sel:[1,0]
	v_mov_b32_e32 v75, v77
	v_fmac_f32_e32 v29, 0xba000000, v14
	v_fmac_f32_e32 v30, 0xba000000, v14
	v_mul_f32_e32 v12, v28, v28
	v_pk_add_f32 v[74:75], v[78:79], v[74:75]
	v_fmac_f32_e32 v31, 0xba000000, v14
	v_pk_fma_f32 v[76:77], v[28:29], v[28:29], v[12:13] op_sel_hi:[1,1,0]
	v_mul_f32_e32 v12, v30, v30
	v_pk_add_f32 v[64:65], v[64:65], v[64:65] op_sel_hi:[0,1]
	v_pk_add_f32 v[74:75], v[74:75], v[74:75] op_sel_hi:[0,1]
	v_pk_fma_f32 v[78:79], v[30:31], v[30:31], v[12:13] op_sel_hi:[1,1,0]
	v_fmac_f32_e32 v25, 0xba000000, v14
	v_fmac_f32_e32 v27, 0xba000000, v14
	v_fmac_f32_e32 v21, 0xba000000, v14
	v_fmac_f32_e32 v23, 0xba000000, v14
	v_mul_f32_e32 v76, v23, v23
	v_mul_f32_e32 v78, v21, v21
	v_mul_f32_e32 v74, v27, v27
	v_mul_f32_e32 v64, v25, v25
	v_pk_add_f32 v[76:77], v[76:77], v[78:79]
	v_pk_add_f32 v[64:65], v[74:75], v[64:65]
	v_fmac_f32_e32 v72, 0xba000000, v14
	v_pk_add_f32 v[64:65], v[76:77], v[64:65]
	v_fmac_f32_e32 v73, 0xba000000, v14
	v_fmac_f32_e32 v61, 0xba000000, v14
	v_pk_add_f32 v[74:75], v[64:65], v[64:65] op_sel_hi:[0,1]
	v_fmac_f32_e32 v60, 0xba000000, v14
	v_mov_b32_e32 v64, v61
	v_mov_b32_e32 v65, v73
	v_mov_b32_e32 v61, v72
	v_pk_mul_f32 v[76:77], v[64:65], v[64:65]
	v_pk_mul_f32 v[72:73], v[60:61], v[60:61]
	v_fmac_f32_e32 v16, 0xba000000, v14
	v_pk_mov_b32 v[78:79], v[72:73], v[76:77] op_sel:[1,0]
	v_mov_b32_e32 v73, v77
	v_fmac_f32_e32 v17, 0xba000000, v14
	v_fmac_f32_e32 v18, 0xba000000, v14
	v_mul_f32_e32 v12, v16, v16
	v_pk_add_f32 v[72:73], v[78:79], v[72:73]
	v_fmac_f32_e32 v19, 0xba000000, v14
	v_pk_fma_f32 v[76:77], v[16:17], v[16:17], v[12:13] op_sel_hi:[1,1,0]
	v_mul_f32_e32 v12, v18, v18
	v_pk_add_f32 v[72:73], v[72:73], v[72:73] op_sel_hi:[0,1]
	v_pk_fma_f32 v[78:79], v[18:19], v[18:19], v[12:13] op_sel_hi:[1,1,0]
	v_fmac_f32_e32 v13, 0xba000000, v14
	v_fmac_f32_e32 v15, 0xba000000, v14
	v_fmac_f32_e32 v11, 0xba000000, v14
	v_fmac_f32_e32 v10, 0xba000000, v14
	v_mul_f32_e32 v72, v15, v15
	v_mul_f32_e32 v74, v13, v13
	v_mul_f32_e32 v76, v10, v10
	v_mul_f32_e32 v78, v11, v11
	v_pk_add_f32 v[72:73], v[72:73], v[74:75]
	v_lshlrev_b32_e32 v74, 2, v1
	v_pk_add_f32 v[76:77], v[76:77], v[78:79]
	v_ashrrev_i32_e32 v75, 31, v74
	v_pk_add_f32 v[72:73], v[76:77], v[72:73]
	v_lshlrev_b64 v[76:77], 2, v[74:75]
	v_lshl_add_u64 v[80:81], s[12:13], 0, v[76:77]
	v_lshl_add_u64 v[78:79], s[14:15], 0, v[76:77]
	s_nop 1
	v_mov_b64_e32 v[84:85], v[180:181]
	v_mov_b64_e32 v[86:87], v[182:183]
	s_nop 1
	v_mov_b64_e32 v[96:97], v[212:213]
	v_mov_b64_e32 v[98:99], v[214:215]
	v_add_f32_e32 v12, v72, v73
	ds_bpermute_b32 v14, v90, v12
	s_waitcnt lgkmcnt(0)
	v_add_f32_e32 v12, v12, v14
	ds_bpermute_b32 v14, v91, v12
	s_waitcnt lgkmcnt(0)
	v_add_f32_e32 v12, v12, v14
	ds_bpermute_b32 v14, v92, v12
	s_waitcnt lgkmcnt(0)
	v_add_f32_e32 v12, v12, v14
	ds_bpermute_b32 v14, v93, v12
	s_waitcnt lgkmcnt(0)
	v_add_f32_e32 v12, v12, v14
	ds_bpermute_b32 v14, v94, v12
	s_waitcnt lgkmcnt(0)
	v_add_f32_e32 v12, v12, v14
	ds_bpermute_b32 v14, v95, v12
	s_waitcnt lgkmcnt(0)
	v_add_f32_e32 v12, v12, v14
	v_fmamk_f32 v12, v12, 0x3a000000, v250
	v_cmp_gt_f32_e32 vcc, s96, v12
	v_mul_f32_e32 v14, 0x4f800000, v12
	s_nop 0
	v_cndmask_b32_e32 v12, v12, v14, vcc
	v_sqrt_f32_e32 v14, v12
	s_nop 0
	v_add_u32_e32 v20, -1, v14
	v_fma_f32 v22, -v20, v14, v12
	v_cmp_ge_f32_e64 s[10:11], 0, v22
	v_add_u32_e32 v22, 1, v14
	s_nop 0
	v_cndmask_b32_e64 v20, v14, v20, s[10:11]
	v_fma_f32 v14, -v22, v14, v12
	v_cmp_lt_f32_e64 s[10:11], 0, v14
	s_nop 1
	v_cndmask_b32_e64 v14, v20, v22, s[10:11]
	v_mul_f32_e32 v20, 0x37800000, v14
	v_cndmask_b32_e32 v14, v14, v20, vcc
	v_cmp_class_f32_e32 vcc, v12, v251
	s_nop 1
	v_cndmask_b32_e32 v12, v14, v12, vcc
	v_div_scale_f32 v14, s[8:9], v12, v12, 1.0
	v_rcp_f32_e32 v20, v14
	s_mov_b64 s[8:9], 0x25d1e000
	v_fma_f32 v22, -v14, v20, 1.0
	v_fmac_f32_e32 v20, v22, v20
	v_div_scale_f32 v22, vcc, 1.0, v12, 1.0
	v_mul_f32_e32 v24, v22, v20
	v_fma_f32 v26, -v14, v24, v22
	v_fmac_f32_e32 v24, v26, v20
	v_fma_f32 v14, -v14, v24, v22
	v_div_fmas_f32 v14, v14, v20, v24
	v_div_fixup_f32 v14, v14, v12, 1.0
	v_pk_mul_f32 v[56:57], v[56:57], v[14:15] op_sel_hi:[1,0]
	v_pk_mul_f32 v[58:59], v[58:59], v[14:15] op_sel_hi:[1,0]
	s_waitcnt vmcnt(0)
	v_pk_fma_f32 v[96:97], v[84:85], v[56:57], v[96:97]
	v_lshl_add_u64 v[56:57], s[40:41], 0, v[76:77]
	v_pk_fma_f32 v[98:99], v[86:87], v[58:59], v[98:99]
	v_lshl_add_u64 v[86:87], v[56:57], 0, s[8:9]
	s_mov_b32 s8, 0x25d1f000
	v_add_co_u32_e32 v72, vcc, s8, v56
	v_lshl_add_u64 v[84:85], s[20:21], 0, v[76:77]
	s_nop 0
	v_addc_co_u32_e32 v73, vcc, 0, v57, vcc
	global_load_dwordx4 v[56:59], v[84:85], off
	v_lshl_add_u64 v[76:77], s[18:19], 0, v[76:77]
	global_load_dwordx4 v[100:103], v[76:77], off
	s_mov_b64 s[8:9], 0xcc1b000
	global_store_dwordx4 v[72:73], v[96:99], off offset:-4096
	v_pk_mul_f32 v[66:67], v[66:67], v[14:15] op_sel_hi:[1,0]
	v_pk_mul_f32 v[62:63], v[62:63], v[14:15] op_sel_hi:[1,0]
	v_pk_mul_f32 v[70:71], v[70:71], v[14:15] op_sel_hi:[1,0]
	v_pk_mul_f32 v[68:69], v[68:69], v[14:15] op_sel_hi:[1,0]
	v_pk_mul_f32 v[30:31], v[30:31], v[14:15] op_sel_hi:[1,0]
	v_pk_mul_f32 v[28:29], v[28:29], v[14:15] op_sel_hi:[1,0]
	v_mov_b32_e32 v24, v27
	v_pk_mul_f32 v[24:25], v[24:25], v[14:15] op_sel_hi:[1,0]
	v_pk_mul_f32 v[64:65], v[64:65], v[14:15] op_sel_hi:[1,0]
	v_pk_mul_f32 v[60:61], v[60:61], v[14:15] op_sel_hi:[1,0]
	v_pk_mul_f32 v[18:19], v[18:19], v[14:15] op_sel_hi:[1,0]
	v_pk_mul_f32 v[16:17], v[16:17], v[14:15] op_sel_hi:[1,0]
	v_pk_mul_f32 v[10:11], v[10:11], v[14:15] op_sel_hi:[1,0]
	s_waitcnt vmcnt(2)
	v_pk_add_f32 v[58:59], v[58:59], 1.0 op_sel_hi:[1,0]
	v_pk_add_f32 v[88:89], v[56:57], 1.0 op_sel_hi:[1,0]
	s_waitcnt vmcnt(1)
	v_pk_fma_f32 v[56:57], v[58:59], v[98:99], v[102:103]
	v_pk_fma_f32 v[58:59], v[88:89], v[96:97], v[100:101]
	v_lshl_add_u64 v[96:97], v[74:75], 1, s[16:17]
	s_nop 0
	s_nop 0
	s_nop 0
	s_nop 0
	s_nop 0
	v_cvt_pk_bf16_f32 v88, v58, v59
	s_nop 0
	s_nop 0
	s_nop 0
	s_nop 0
	s_nop 0
	v_lshl_add_u64 v[74:75], v[96:97], 0, s[8:9]
	v_add_co_u32_e32 v96, vcc, s61, v96
	v_cvt_pk_bf16_f32 v89, v56, v57
	s_nop 0
	v_addc_co_u32_e32 v97, vcc, 0, v97, vcc
	global_store_dwordx2 v[96:97], v[88:89], off
	s_nop 1
	v_mov_b64_e32 v[96:97], v[184:185]
	v_mov_b64_e32 v[98:99], v[186:187]
	s_nop 0
	s_nop 1
	v_mov_b64_e32 v[100:101], v[216:217]
	v_mov_b64_e32 v[102:103], v[218:219]
	s_waitcnt vmcnt(0)
	v_pk_fma_f32 v[96:97], v[96:97], v[62:63], v[100:101]
	v_pk_fma_f32 v[98:99], v[98:99], v[66:67], v[102:103]
	global_store_dwordx4 v[86:87], v[96:99], off offset:1024
	global_load_dwordx4 v[100:103], v[84:85], off offset:1024
	global_load_dwordx4 v[104:107], v[76:77], off offset:1024
	s_waitcnt vmcnt(1)
	v_pk_add_f32 v[66:67], v[100:101], 1.0 op_sel_hi:[1,0]
	s_waitcnt vmcnt(0)
	v_pk_fma_f32 v[66:67], v[66:67], v[96:97], v[104:105]
	v_pk_add_f32 v[62:63], v[102:103], 1.0 op_sel_hi:[1,0]
	v_pk_fma_f32 v[62:63], v[62:63], v[98:99], v[106:107]
	v_cvt_pk_bf16_f32 v88, v66, v67
	v_cvt_pk_bf16_f32 v89, v62, v63
	global_store_dwordx2 v[74:75], v[88:89], off offset:512
	s_nop 1
	v_mov_b64_e32 v[96:97], v[188:189]
	v_mov_b64_e32 v[98:99], v[190:191]
	s_nop 1
	v_mov_b64_e32 v[100:101], v[220:221]
	v_mov_b64_e32 v[102:103], v[222:223]
	s_waitcnt vmcnt(0)
	v_pk_fma_f32 v[96:97], v[96:97], v[68:69], v[100:101]
	v_pk_fma_f32 v[98:99], v[98:99], v[70:71], v[102:103]
	global_store_dwordx4 v[86:87], v[96:99], off offset:2048
	global_load_dwordx4 v[68:71], v[84:85], off offset:2048
	global_load_dwordx4 v[100:103], v[76:77], off offset:2048
	s_waitcnt vmcnt(1)
	v_pk_add_f32 v[70:71], v[70:71], 1.0 op_sel_hi:[1,0]
	v_pk_add_f32 v[88:89], v[68:69], 1.0 op_sel_hi:[1,0]
	s_waitcnt vmcnt(0)
	v_pk_fma_f32 v[68:69], v[70:71], v[98:99], v[102:103]
	v_pk_fma_f32 v[70:71], v[88:89], v[96:97], v[100:101]
	s_nop 0
	s_nop 0
	s_nop 0
	s_nop 0
	s_nop 0
	s_nop 0
	v_cvt_pk_bf16_f32 v88, v70, v71
	s_nop 0
	s_nop 0
	s_nop 0
	s_nop 0
	s_nop 0
	v_cvt_pk_bf16_f32 v89, v68, v69
	global_store_dwordx2 v[74:75], v[88:89], off offset:1024
	s_nop 1
	v_mov_b64_e32 v[96:97], v[192:193]
	v_mov_b64_e32 v[98:99], v[194:195]
	s_nop 1
	v_mov_b64_e32 v[100:101], v[236:237]
	v_mov_b64_e32 v[102:103], v[238:239]
	v_add_co_u32_e32 v80, vcc, s82, v80
	s_waitcnt vmcnt(0)
	v_pk_fma_f32 v[96:97], v[96:97], v[28:29], v[100:101]
	v_pk_fma_f32 v[98:99], v[98:99], v[30:31], v[102:103]
	global_store_dwordx4 v[86:87], v[96:99], off offset:3072
	global_load_dwordx4 v[28:31], v[84:85], off offset:3072
	s_nop 0
	global_load_dwordx4 v[86:89], v[76:77], off offset:3072
	v_addc_co_u32_e32 v81, vcc, 0, v81, vcc
	v_add_co_u32_e32 v78, vcc, s82, v78
	s_waitcnt vmcnt(1)
	v_pk_add_f32 v[30:31], v[30:31], 1.0 op_sel_hi:[1,0]
	v_pk_add_f32 v[100:101], v[28:29], 1.0 op_sel_hi:[1,0]
	s_waitcnt vmcnt(0)
	v_pk_fma_f32 v[28:29], v[30:31], v[98:99], v[88:89]
	v_pk_fma_f32 v[30:31], v[100:101], v[96:97], v[86:87]
	v_addc_co_u32_e32 v79, vcc, 0, v79, vcc
	s_nop 0
	s_nop 0
	s_nop 0
	s_nop 0
	s_nop 0
	v_cvt_pk_bf16_f32 v86, v30, v31
	s_nop 0
	s_nop 0
	s_nop 0
	s_nop 0
	s_nop 0
	v_cvt_pk_bf16_f32 v87, v28, v29
	global_store_dwordx2 v[74:75], v[86:87], off offset:1536
	s_nop 1
	v_mov_b64_e32 v[86:87], v[196:197]
	v_mov_b64_e32 v[88:89], v[198:199]
	s_nop 1
	v_mov_b64_e32 v[96:97], v[240:241]
	v_mov_b64_e32 v[98:99], v[242:243]
	v_add_co_u32_e32 v84, vcc, s82, v84
	v_mov_b32_e32 v20, v23
	s_nop 0
	v_addc_co_u32_e32 v85, vcc, 0, v85, vcc
	v_pk_mul_f32 v[20:21], v[20:21], v[14:15] op_sel_hi:[1,0]
	v_add_co_u32_e32 v76, vcc, s82, v76
	s_waitcnt vmcnt(0)
	v_pk_fma_f32 v[22:23], v[20:21], v[86:87], v[96:97]
	v_pk_fma_f32 v[24:25], v[24:25], v[88:89], v[98:99]
	global_load_dwordx4 v[86:89], v[84:85], off
	v_addc_co_u32_e32 v77, vcc, 0, v77, vcc
	global_load_dwordx4 v[96:99], v[76:77], off
	s_waitcnt vmcnt(1)
	v_pk_add_f32 v[26:27], v[86:87], 1.0 op_sel_hi:[1,0]
	global_store_dwordx4 v[72:73], v[22:25], off
	v_pk_add_f32 v[20:21], v[88:89], 1.0 op_sel_hi:[1,0]
	s_waitcnt vmcnt(1)
	v_pk_fma_f32 v[22:23], v[22:23], v[26:27], v[96:97]
	v_pk_fma_f32 v[20:21], v[24:25], v[20:21], v[98:99]
	v_cvt_pk_bf16_f32 v24, v22, v23
	v_cvt_pk_bf16_f32 v25, v20, v21
	global_store_dwordx2 v[74:75], v[24:25], off offset:2048
	s_nop 1
	v_mov_b64_e32 v[24:25], v[200:201]
	v_mov_b64_e32 v[26:27], v[202:203]
	s_nop 0
	s_nop 1
	v_mov_b64_e32 v[86:87], v[128:129]
	v_mov_b64_e32 v[88:89], v[130:131]
	s_waitcnt vmcnt(0)
	v_pk_fma_f32 v[86:87], v[60:61], v[24:25], v[86:87]
	v_pk_fma_f32 v[88:89], v[64:65], v[26:27], v[88:89]
	global_store_dwordx4 v[72:73], v[86:89], off offset:1024
	global_load_dwordx4 v[24:27], v[84:85], off offset:1024
	global_load_dwordx4 v[96:99], v[76:77], off offset:1024
	s_waitcnt vmcnt(1)
	v_pk_add_f32 v[26:27], v[26:27], 1.0 op_sel_hi:[1,0]
	v_pk_add_f32 v[60:61], v[24:25], 1.0 op_sel_hi:[1,0]
	s_waitcnt vmcnt(0)
	v_pk_fma_f32 v[24:25], v[88:89], v[26:27], v[98:99]
	v_pk_fma_f32 v[26:27], v[86:87], v[60:61], v[96:97]
	v_cvt_pk_bf16_f32 v60, v26, v27
	v_cvt_pk_bf16_f32 v61, v24, v25
	global_store_dwordx2 v[74:75], v[60:61], off offset:2560
	s_nop 1
	v_mov_b64_e32 v[86:87], v[204:205]
	v_mov_b64_e32 v[88:89], v[206:207]
	s_nop 1
	v_mov_b64_e32 v[96:97], v[132:133]
	v_mov_b64_e32 v[98:99], v[134:135]
	s_waitcnt vmcnt(0)
	v_pk_fma_f32 v[86:87], v[16:17], v[86:87], v[96:97]
	v_pk_fma_f32 v[88:89], v[18:19], v[88:89], v[98:99]
	global_store_dwordx4 v[72:73], v[86:89], off offset:2048
	global_load_dwordx4 v[16:19], v[84:85], off offset:2048
	global_load_dwordx4 v[96:99], v[76:77], off offset:2048
	s_waitcnt vmcnt(1)
	v_pk_add_f32 v[18:19], v[18:19], 1.0 op_sel_hi:[1,0]
	v_pk_add_f32 v[60:61], v[16:17], 1.0 op_sel_hi:[1,0]
	s_waitcnt vmcnt(0)
	v_pk_fma_f32 v[16:17], v[88:89], v[18:19], v[98:99]
	v_pk_fma_f32 v[18:19], v[86:87], v[60:61], v[96:97]
	v_cvt_pk_bf16_f32 v60, v18, v19
	v_cvt_pk_bf16_f32 v61, v16, v17
	global_store_dwordx2 v[74:75], v[60:61], off offset:3072
	s_nop 1
	v_mov_b64_e32 v[86:87], v[208:209]
	v_mov_b64_e32 v[88:89], v[210:211]
	s_nop 0
	s_nop 1
	v_mov_b64_e32 v[78:79], v[140:141]
	v_mov_b64_e32 v[80:81], v[142:143]
	v_mov_b32_e32 v12, v15
	v_pk_mul_f32 v[60:61], v[12:13], v[14:15] op_sel_hi:[1,0]
	s_waitcnt vmcnt(0)
	v_pk_fma_f32 v[12:13], v[10:11], v[86:87], v[78:79]
	v_pk_fma_f32 v[14:15], v[60:61], v[88:89], v[80:81]
	global_store_dwordx4 v[72:73], v[12:15], off offset:3072
	global_load_dwordx4 v[78:81], v[84:85], off offset:3072
	s_nop 0
	global_load_dwordx4 v[84:87], v[76:77], off offset:3072
	s_waitcnt vmcnt(1)
	v_pk_add_f32 v[60:61], v[78:79], 1.0 op_sel_hi:[1,0]
	v_pk_add_f32 v[10:11], v[80:81], 1.0 op_sel_hi:[1,0]
	s_waitcnt vmcnt(0)
	v_pk_fma_f32 v[12:13], v[12:13], v[60:61], v[84:85]
	v_pk_fma_f32 v[10:11], v[14:15], v[10:11], v[86:87]
	v_cvt_pk_bf16_f32 v14, v12, v13
	s_nop 0
	s_nop 0
	s_nop 0
	s_nop 0
	s_nop 0
	v_cvt_pk_bf16_f32 v15, v10, v11
	global_store_dwordx2 v[74:75], v[14:15], off offset:3584
	s_nop 0
	v_lshl_add_u32 v103, v1, 4, 0
	ds_read_b128 v[72:75], v103
	v_add_u32_e32 v80, 0x18400, v103
	s_waitcnt lgkmcnt(0)
	v_pk_fma_f32 v[14:15], v[4:5], v[72:73], 0 op_sel_hi:[1,1,0]
	v_pk_fma_f32 v[60:61], v[58:59], v[72:73], 0 op_sel_hi:[1,1,0]
	v_pk_fma_f32 v[14:15], v[2:3], v[74:75], v[14:15]
	v_pk_fma_f32 v[60:61], v[56:57], v[74:75], v[60:61]
	ds_read_b128 v[72:75], v103 offset:1024
	s_waitcnt lgkmcnt(0)
	v_pk_fma_f32 v[14:15], v[8:9], v[72:73], v[14:15]
	v_pk_fma_f32 v[60:61], v[66:67], v[72:73], v[60:61]
	v_pk_fma_f32 v[14:15], v[6:7], v[74:75], v[14:15]
	v_pk_fma_f32 v[60:61], v[62:63], v[74:75], v[60:61]
	ds_read_b128 v[72:75], v103 offset:2048
	s_waitcnt lgkmcnt(0)
	v_pk_fma_f32 v[14:15], v[34:35], v[72:73], v[14:15]
	v_pk_fma_f32 v[60:61], v[70:71], v[72:73], v[60:61]
	v_pk_fma_f32 v[14:15], v[32:33], v[74:75], v[14:15]
	v_pk_fma_f32 v[60:61], v[68:69], v[74:75], v[60:61]
	ds_read_b128 v[72:75], v103 offset:3072
	s_waitcnt lgkmcnt(0)
	v_pk_fma_f32 v[14:15], v[38:39], v[72:73], v[14:15]
	v_pk_fma_f32 v[60:61], v[30:31], v[72:73], v[60:61]
	v_pk_fma_f32 v[14:15], v[36:37], v[74:75], v[14:15]
	v_pk_fma_f32 v[60:61], v[28:29], v[74:75], v[60:61]
	ds_read_b128 v[72:75], v103 offset:4096
	s_waitcnt lgkmcnt(0)
	v_pk_fma_f32 v[14:15], v[42:43], v[72:73], v[14:15]
	v_pk_fma_f32 v[60:61], v[22:23], v[72:73], v[60:61]
	v_pk_fma_f32 v[14:15], v[40:41], v[74:75], v[14:15]
	v_pk_fma_f32 v[60:61], v[20:21], v[74:75], v[60:61]
	ds_read_b128 v[72:75], v103 offset:5120
	s_waitcnt lgkmcnt(0)
	v_pk_fma_f32 v[14:15], v[46:47], v[72:73], v[14:15]
	v_pk_fma_f32 v[60:61], v[26:27], v[72:73], v[60:61]
	v_pk_fma_f32 v[14:15], v[44:45], v[74:75], v[14:15]
	v_pk_fma_f32 v[60:61], v[24:25], v[74:75], v[60:61]
	ds_read_b128 v[72:75], v103 offset:6144
	s_waitcnt lgkmcnt(0)
	v_pk_fma_f32 v[14:15], v[50:51], v[72:73], v[14:15]
	v_pk_fma_f32 v[60:61], v[18:19], v[72:73], v[60:61]
	v_pk_fma_f32 v[14:15], v[48:49], v[74:75], v[14:15]
	v_pk_fma_f32 v[60:61], v[16:17], v[74:75], v[60:61]
	ds_read_b128 v[72:75], v103 offset:7168
	s_waitcnt lgkmcnt(0)
	v_pk_fma_f32 v[14:15], v[54:55], v[72:73], v[14:15]
	v_pk_fma_f32 v[60:61], v[12:13], v[72:73], v[60:61]
	v_pk_fma_f32 v[14:15], v[52:53], v[74:75], v[14:15]
	v_pk_fma_f32 v[60:61], v[10:11], v[74:75], v[60:61]
	v_add_f32_e32 v81, v14, v15
	v_add_f32_e32 v14, v60, v61
	ds_read_b128 v[72:75], v103 offset:8192
	s_waitcnt lgkmcnt(0)
	v_pk_fma_f32 v[60:61], v[4:5], v[72:73], 0 op_sel_hi:[1,1,0]
	v_pk_fma_f32 v[64:65], v[58:59], v[72:73], 0 op_sel_hi:[1,1,0]
	v_pk_fma_f32 v[60:61], v[2:3], v[74:75], v[60:61]
	v_pk_fma_f32 v[64:65], v[56:57], v[74:75], v[64:65]
	ds_read_b128 v[72:75], v103 offset:9216
	s_waitcnt lgkmcnt(0)
	v_pk_fma_f32 v[60:61], v[8:9], v[72:73], v[60:61]
	v_pk_fma_f32 v[64:65], v[66:67], v[72:73], v[64:65]
	v_pk_fma_f32 v[60:61], v[6:7], v[74:75], v[60:61]
	v_pk_fma_f32 v[64:65], v[62:63], v[74:75], v[64:65]
	ds_read_b128 v[72:75], v103 offset:10240
	s_waitcnt lgkmcnt(0)
	v_pk_fma_f32 v[60:61], v[34:35], v[72:73], v[60:61]
	v_pk_fma_f32 v[64:65], v[70:71], v[72:73], v[64:65]
	v_pk_fma_f32 v[60:61], v[32:33], v[74:75], v[60:61]
	v_pk_fma_f32 v[64:65], v[68:69], v[74:75], v[64:65]
	ds_read_b128 v[72:75], v103 offset:11264
	s_waitcnt lgkmcnt(0)
	v_pk_fma_f32 v[60:61], v[38:39], v[72:73], v[60:61]
	v_pk_fma_f32 v[64:65], v[30:31], v[72:73], v[64:65]
	v_pk_fma_f32 v[60:61], v[36:37], v[74:75], v[60:61]
	v_pk_fma_f32 v[64:65], v[28:29], v[74:75], v[64:65]
	ds_read_b128 v[72:75], v103 offset:12288
	s_waitcnt lgkmcnt(0)
	v_pk_fma_f32 v[60:61], v[42:43], v[72:73], v[60:61]
	v_pk_fma_f32 v[64:65], v[22:23], v[72:73], v[64:65]
	v_pk_fma_f32 v[60:61], v[40:41], v[74:75], v[60:61]
	v_pk_fma_f32 v[64:65], v[20:21], v[74:75], v[64:65]
	ds_read_b128 v[72:75], v103 offset:13312
	s_waitcnt lgkmcnt(0)
	v_pk_fma_f32 v[60:61], v[46:47], v[72:73], v[60:61]
	v_pk_fma_f32 v[64:65], v[26:27], v[72:73], v[64:65]
	v_pk_fma_f32 v[60:61], v[44:45], v[74:75], v[60:61]
	v_pk_fma_f32 v[64:65], v[24:25], v[74:75], v[64:65]
	ds_read_b128 v[72:75], v103 offset:14336
	s_waitcnt lgkmcnt(0)
	v_pk_fma_f32 v[60:61], v[50:51], v[72:73], v[60:61]
	v_pk_fma_f32 v[64:65], v[18:19], v[72:73], v[64:65]
	v_pk_fma_f32 v[60:61], v[48:49], v[74:75], v[60:61]
	v_pk_fma_f32 v[64:65], v[16:17], v[74:75], v[64:65]
	ds_read_b128 v[72:75], v103 offset:15360
	s_waitcnt lgkmcnt(0)
	v_pk_fma_f32 v[60:61], v[54:55], v[72:73], v[60:61]
	v_pk_fma_f32 v[64:65], v[12:13], v[72:73], v[64:65]
	v_pk_fma_f32 v[60:61], v[52:53], v[74:75], v[60:61]
	v_pk_fma_f32 v[64:65], v[10:11], v[74:75], v[64:65]
	v_add_f32_e32 v82, v60, v61
	v_add_f32_e32 v15, v64, v65
	ds_read_b128 v[72:75], v103 offset:16384
	s_waitcnt lgkmcnt(0)
	v_pk_fma_f32 v[60:61], v[4:5], v[72:73], 0 op_sel_hi:[1,1,0]
	v_pk_fma_f32 v[64:65], v[58:59], v[72:73], 0 op_sel_hi:[1,1,0]
	v_pk_fma_f32 v[60:61], v[2:3], v[74:75], v[60:61]
	v_pk_fma_f32 v[64:65], v[56:57], v[74:75], v[64:65]
	ds_read_b128 v[72:75], v103 offset:17408
	s_waitcnt lgkmcnt(0)
	v_pk_fma_f32 v[60:61], v[8:9], v[72:73], v[60:61]
	v_pk_fma_f32 v[64:65], v[66:67], v[72:73], v[64:65]
	v_pk_fma_f32 v[60:61], v[6:7], v[74:75], v[60:61]
	v_pk_fma_f32 v[64:65], v[62:63], v[74:75], v[64:65]
	ds_read_b128 v[72:75], v103 offset:18432
	s_waitcnt lgkmcnt(0)
	v_pk_fma_f32 v[60:61], v[34:35], v[72:73], v[60:61]
	v_pk_fma_f32 v[64:65], v[70:71], v[72:73], v[64:65]
	v_pk_fma_f32 v[60:61], v[32:33], v[74:75], v[60:61]
	v_pk_fma_f32 v[64:65], v[68:69], v[74:75], v[64:65]
	ds_read_b128 v[72:75], v103 offset:19456
	s_waitcnt lgkmcnt(0)
	v_pk_fma_f32 v[60:61], v[38:39], v[72:73], v[60:61]
	v_pk_fma_f32 v[64:65], v[30:31], v[72:73], v[64:65]
	v_pk_fma_f32 v[60:61], v[36:37], v[74:75], v[60:61]
	v_pk_fma_f32 v[64:65], v[28:29], v[74:75], v[64:65]
	ds_read_b128 v[72:75], v103 offset:20480
	s_waitcnt lgkmcnt(0)
	v_pk_fma_f32 v[60:61], v[42:43], v[72:73], v[60:61]
	v_pk_fma_f32 v[64:65], v[22:23], v[72:73], v[64:65]
	v_pk_fma_f32 v[60:61], v[40:41], v[74:75], v[60:61]
	v_pk_fma_f32 v[64:65], v[20:21], v[74:75], v[64:65]
	ds_read_b128 v[72:75], v103 offset:21504
	s_waitcnt lgkmcnt(0)
	v_pk_fma_f32 v[60:61], v[46:47], v[72:73], v[60:61]
	v_pk_fma_f32 v[64:65], v[26:27], v[72:73], v[64:65]
	v_pk_fma_f32 v[60:61], v[44:45], v[74:75], v[60:61]
	v_pk_fma_f32 v[64:65], v[24:25], v[74:75], v[64:65]
	ds_read_b128 v[72:75], v103 offset:22528
	s_waitcnt lgkmcnt(0)
	v_pk_fma_f32 v[60:61], v[50:51], v[72:73], v[60:61]
	v_pk_fma_f32 v[64:65], v[18:19], v[72:73], v[64:65]
	v_pk_fma_f32 v[60:61], v[48:49], v[74:75], v[60:61]
	v_pk_fma_f32 v[64:65], v[16:17], v[74:75], v[64:65]
	ds_read_b128 v[72:75], v103 offset:23552
	s_waitcnt lgkmcnt(0)
	v_pk_fma_f32 v[60:61], v[54:55], v[72:73], v[60:61]
	v_pk_fma_f32 v[64:65], v[12:13], v[72:73], v[64:65]
	v_pk_fma_f32 v[60:61], v[52:53], v[74:75], v[60:61]
	v_pk_fma_f32 v[64:65], v[10:11], v[74:75], v[64:65]
	v_add_f32_e32 v84, v60, v61
	v_add_f32_e32 v60, v64, v65
	ds_read_b128 v[72:75], v103 offset:24576
	s_waitcnt lgkmcnt(0)
	v_pk_fma_f32 v[64:65], v[4:5], v[72:73], 0 op_sel_hi:[1,1,0]
	v_pk_fma_f32 v[72:73], v[58:59], v[72:73], 0 op_sel_hi:[1,1,0]
	v_pk_fma_f32 v[64:65], v[2:3], v[74:75], v[64:65]
	v_pk_fma_f32 v[76:77], v[56:57], v[74:75], v[72:73]
	ds_read_b128 v[72:75], v103 offset:25600
	s_waitcnt lgkmcnt(0)
	v_pk_fma_f32 v[64:65], v[8:9], v[72:73], v[64:65]
	v_pk_fma_f32 v[72:73], v[66:67], v[72:73], v[76:77]
	v_pk_fma_f32 v[64:65], v[6:7], v[74:75], v[64:65]
	v_pk_fma_f32 v[76:77], v[62:63], v[74:75], v[72:73]
	ds_read_b128 v[72:75], v103 offset:26624
	s_waitcnt lgkmcnt(0)
	v_pk_fma_f32 v[64:65], v[34:35], v[72:73], v[64:65]
	v_pk_fma_f32 v[72:73], v[70:71], v[72:73], v[76:77]
	v_pk_fma_f32 v[64:65], v[32:33], v[74:75], v[64:65]
	v_pk_fma_f32 v[76:77], v[68:69], v[74:75], v[72:73]
	ds_read_b128 v[72:75], v103 offset:27648
	s_waitcnt lgkmcnt(0)
	v_pk_fma_f32 v[64:65], v[38:39], v[72:73], v[64:65]
	v_pk_fma_f32 v[72:73], v[30:31], v[72:73], v[76:77]
	v_pk_fma_f32 v[64:65], v[36:37], v[74:75], v[64:65]
	v_pk_fma_f32 v[76:77], v[28:29], v[74:75], v[72:73]
	ds_read_b128 v[72:75], v103 offset:28672
	s_waitcnt lgkmcnt(0)
	v_pk_fma_f32 v[64:65], v[42:43], v[72:73], v[64:65]
	v_pk_fma_f32 v[72:73], v[22:23], v[72:73], v[76:77]
	v_pk_fma_f32 v[64:65], v[40:41], v[74:75], v[64:65]
	v_pk_fma_f32 v[76:77], v[20:21], v[74:75], v[72:73]
	ds_read_b128 v[72:75], v103 offset:29696
	s_waitcnt lgkmcnt(0)
	v_pk_fma_f32 v[64:65], v[46:47], v[72:73], v[64:65]
	v_pk_fma_f32 v[72:73], v[26:27], v[72:73], v[76:77]
	v_pk_fma_f32 v[64:65], v[44:45], v[74:75], v[64:65]
	v_pk_fma_f32 v[76:77], v[24:25], v[74:75], v[72:73]
	ds_read_b128 v[72:75], v103 offset:30720
	s_waitcnt lgkmcnt(0)
	v_pk_fma_f32 v[64:65], v[50:51], v[72:73], v[64:65]
	v_pk_fma_f32 v[72:73], v[18:19], v[72:73], v[76:77]
	v_pk_fma_f32 v[64:65], v[48:49], v[74:75], v[64:65]
	v_pk_fma_f32 v[76:77], v[16:17], v[74:75], v[72:73]
	ds_read_b128 v[72:75], v103 offset:31744
	s_waitcnt lgkmcnt(0)
	v_pk_fma_f32 v[64:65], v[54:55], v[72:73], v[64:65]
	v_pk_fma_f32 v[72:73], v[12:13], v[72:73], v[76:77]
	v_pk_fma_f32 v[64:65], v[52:53], v[74:75], v[64:65]
	v_pk_fma_f32 v[72:73], v[10:11], v[74:75], v[72:73]
	v_add_f32_e32 v85, v64, v65
	v_add_f32_e32 v61, v72, v73
	ds_read_b128 v[72:75], v103 offset:32768
	s_waitcnt lgkmcnt(0)
	v_pk_fma_f32 v[64:65], v[4:5], v[72:73], 0 op_sel_hi:[1,1,0]
	v_pk_fma_f32 v[72:73], v[58:59], v[72:73], 0 op_sel_hi:[1,1,0]
	v_pk_fma_f32 v[64:65], v[2:3], v[74:75], v[64:65]
	v_pk_fma_f32 v[76:77], v[56:57], v[74:75], v[72:73]
	ds_read_b128 v[72:75], v103 offset:33792
	s_waitcnt lgkmcnt(0)
	v_pk_fma_f32 v[64:65], v[8:9], v[72:73], v[64:65]
	v_pk_fma_f32 v[72:73], v[66:67], v[72:73], v[76:77]
	v_pk_fma_f32 v[64:65], v[6:7], v[74:75], v[64:65]
	v_pk_fma_f32 v[76:77], v[62:63], v[74:75], v[72:73]
	ds_read_b128 v[72:75], v103 offset:34816
	s_waitcnt lgkmcnt(0)
	v_pk_fma_f32 v[64:65], v[34:35], v[72:73], v[64:65]
	v_pk_fma_f32 v[72:73], v[70:71], v[72:73], v[76:77]
	v_pk_fma_f32 v[64:65], v[32:33], v[74:75], v[64:65]
	v_pk_fma_f32 v[76:77], v[68:69], v[74:75], v[72:73]
	ds_read_b128 v[72:75], v103 offset:35840
	s_waitcnt lgkmcnt(0)
	v_pk_fma_f32 v[64:65], v[38:39], v[72:73], v[64:65]
	v_pk_fma_f32 v[72:73], v[30:31], v[72:73], v[76:77]
	v_pk_fma_f32 v[64:65], v[36:37], v[74:75], v[64:65]
	v_pk_fma_f32 v[76:77], v[28:29], v[74:75], v[72:73]
	ds_read_b128 v[72:75], v103 offset:36864
	s_waitcnt lgkmcnt(0)
	v_pk_fma_f32 v[64:65], v[42:43], v[72:73], v[64:65]
	v_pk_fma_f32 v[72:73], v[22:23], v[72:73], v[76:77]
	v_pk_fma_f32 v[64:65], v[40:41], v[74:75], v[64:65]
	v_pk_fma_f32 v[76:77], v[20:21], v[74:75], v[72:73]
	ds_read_b128 v[72:75], v103 offset:37888
	s_waitcnt lgkmcnt(0)
	v_pk_fma_f32 v[64:65], v[46:47], v[72:73], v[64:65]
	v_pk_fma_f32 v[72:73], v[26:27], v[72:73], v[76:77]
	v_pk_fma_f32 v[64:65], v[44:45], v[74:75], v[64:65]
	v_pk_fma_f32 v[76:77], v[24:25], v[74:75], v[72:73]
	ds_read_b128 v[72:75], v103 offset:38912
	s_waitcnt lgkmcnt(0)
	v_pk_fma_f32 v[64:65], v[50:51], v[72:73], v[64:65]
	v_pk_fma_f32 v[72:73], v[18:19], v[72:73], v[76:77]
	v_pk_fma_f32 v[64:65], v[48:49], v[74:75], v[64:65]
	v_pk_fma_f32 v[76:77], v[16:17], v[74:75], v[72:73]
	ds_read_b128 v[72:75], v103 offset:39936
	s_waitcnt lgkmcnt(0)
	v_pk_fma_f32 v[64:65], v[54:55], v[72:73], v[64:65]
	v_pk_fma_f32 v[72:73], v[12:13], v[72:73], v[76:77]
	v_pk_fma_f32 v[64:65], v[52:53], v[74:75], v[64:65]
	v_pk_fma_f32 v[72:73], v[10:11], v[74:75], v[72:73]
	v_add_f32_e32 v86, v64, v65
	v_add_f32_e32 v64, v72, v73
	ds_read_b128 v[72:75], v103 offset:40960
	s_waitcnt lgkmcnt(0)
	v_pk_fma_f32 v[76:77], v[4:5], v[72:73], 0 op_sel_hi:[1,1,0]
	v_pk_fma_f32 v[72:73], v[58:59], v[72:73], 0 op_sel_hi:[1,1,0]
	v_pk_fma_f32 v[76:77], v[2:3], v[74:75], v[76:77]
	v_pk_fma_f32 v[78:79], v[56:57], v[74:75], v[72:73]
	ds_read_b128 v[72:75], v103 offset:41984
	s_waitcnt lgkmcnt(0)
	v_pk_fma_f32 v[76:77], v[8:9], v[72:73], v[76:77]
	v_pk_fma_f32 v[72:73], v[66:67], v[72:73], v[78:79]
	v_pk_fma_f32 v[76:77], v[6:7], v[74:75], v[76:77]
	v_pk_fma_f32 v[78:79], v[62:63], v[74:75], v[72:73]
	ds_read_b128 v[72:75], v103 offset:43008
	s_waitcnt lgkmcnt(0)
	v_pk_fma_f32 v[76:77], v[34:35], v[72:73], v[76:77]
	v_pk_fma_f32 v[72:73], v[70:71], v[72:73], v[78:79]
	v_pk_fma_f32 v[76:77], v[32:33], v[74:75], v[76:77]
	v_pk_fma_f32 v[78:79], v[68:69], v[74:75], v[72:73]
	ds_read_b128 v[72:75], v103 offset:44032
	s_waitcnt lgkmcnt(0)
	v_pk_fma_f32 v[76:77], v[38:39], v[72:73], v[76:77]
	v_pk_fma_f32 v[72:73], v[30:31], v[72:73], v[78:79]
	v_pk_fma_f32 v[76:77], v[36:37], v[74:75], v[76:77]
	v_pk_fma_f32 v[78:79], v[28:29], v[74:75], v[72:73]
	ds_read_b128 v[72:75], v103 offset:45056
	s_waitcnt lgkmcnt(0)
	v_pk_fma_f32 v[76:77], v[42:43], v[72:73], v[76:77]
	v_pk_fma_f32 v[72:73], v[22:23], v[72:73], v[78:79]
	v_pk_fma_f32 v[76:77], v[40:41], v[74:75], v[76:77]
	v_pk_fma_f32 v[78:79], v[20:21], v[74:75], v[72:73]
	ds_read_b128 v[72:75], v103 offset:46080
	s_waitcnt lgkmcnt(0)
	v_pk_fma_f32 v[76:77], v[46:47], v[72:73], v[76:77]
	v_pk_fma_f32 v[72:73], v[26:27], v[72:73], v[78:79]
	v_pk_fma_f32 v[76:77], v[44:45], v[74:75], v[76:77]
	v_pk_fma_f32 v[78:79], v[24:25], v[74:75], v[72:73]
	ds_read_b128 v[72:75], v103 offset:47104
	s_waitcnt lgkmcnt(0)
	v_pk_fma_f32 v[76:77], v[50:51], v[72:73], v[76:77]
	v_pk_fma_f32 v[72:73], v[18:19], v[72:73], v[78:79]
	v_pk_fma_f32 v[76:77], v[48:49], v[74:75], v[76:77]
	v_pk_fma_f32 v[78:79], v[16:17], v[74:75], v[72:73]
	ds_read_b128 v[72:75], v103 offset:48128
	s_waitcnt lgkmcnt(0)
	v_pk_fma_f32 v[76:77], v[54:55], v[72:73], v[76:77]
	v_pk_fma_f32 v[72:73], v[12:13], v[72:73], v[78:79]
	v_pk_fma_f32 v[76:77], v[52:53], v[74:75], v[76:77]
	v_pk_fma_f32 v[72:73], v[10:11], v[74:75], v[72:73]
	v_add_f32_e32 v87, v76, v77
	v_add_f32_e32 v65, v72, v73
	ds_read_b128 v[72:75], v103 offset:49152
	s_waitcnt lgkmcnt(0)
	v_pk_fma_f32 v[76:77], v[4:5], v[72:73], 0 op_sel_hi:[1,1,0]
	v_pk_fma_f32 v[72:73], v[58:59], v[72:73], 0 op_sel_hi:[1,1,0]
	v_pk_fma_f32 v[76:77], v[2:3], v[74:75], v[76:77]
	v_pk_fma_f32 v[78:79], v[56:57], v[74:75], v[72:73]
	ds_read_b128 v[72:75], v103 offset:50176
	s_waitcnt lgkmcnt(0)
	v_pk_fma_f32 v[76:77], v[8:9], v[72:73], v[76:77]
	v_pk_fma_f32 v[72:73], v[66:67], v[72:73], v[78:79]
	v_pk_fma_f32 v[76:77], v[6:7], v[74:75], v[76:77]
	v_pk_fma_f32 v[78:79], v[62:63], v[74:75], v[72:73]
	ds_read_b128 v[72:75], v103 offset:51200
	s_waitcnt lgkmcnt(0)
	v_pk_fma_f32 v[76:77], v[34:35], v[72:73], v[76:77]
	v_pk_fma_f32 v[72:73], v[70:71], v[72:73], v[78:79]
	v_pk_fma_f32 v[76:77], v[32:33], v[74:75], v[76:77]
	v_pk_fma_f32 v[78:79], v[68:69], v[74:75], v[72:73]
	ds_read_b128 v[72:75], v103 offset:52224
	s_waitcnt lgkmcnt(0)
	v_pk_fma_f32 v[76:77], v[38:39], v[72:73], v[76:77]
	v_pk_fma_f32 v[72:73], v[30:31], v[72:73], v[78:79]
	v_pk_fma_f32 v[76:77], v[36:37], v[74:75], v[76:77]
	v_pk_fma_f32 v[78:79], v[28:29], v[74:75], v[72:73]
	ds_read_b128 v[72:75], v103 offset:53248
	s_waitcnt lgkmcnt(0)
	v_pk_fma_f32 v[76:77], v[42:43], v[72:73], v[76:77]
	v_pk_fma_f32 v[72:73], v[22:23], v[72:73], v[78:79]
	v_pk_fma_f32 v[76:77], v[40:41], v[74:75], v[76:77]
	v_pk_fma_f32 v[78:79], v[20:21], v[74:75], v[72:73]
	ds_read_b128 v[72:75], v103 offset:54272
	s_waitcnt lgkmcnt(0)
	v_pk_fma_f32 v[76:77], v[46:47], v[72:73], v[76:77]
	v_pk_fma_f32 v[72:73], v[26:27], v[72:73], v[78:79]
	v_pk_fma_f32 v[76:77], v[44:45], v[74:75], v[76:77]
	v_pk_fma_f32 v[78:79], v[24:25], v[74:75], v[72:73]
	ds_read_b128 v[72:75], v103 offset:55296
	s_waitcnt lgkmcnt(0)
	v_pk_fma_f32 v[76:77], v[50:51], v[72:73], v[76:77]
	v_pk_fma_f32 v[72:73], v[18:19], v[72:73], v[78:79]
	v_pk_fma_f32 v[76:77], v[48:49], v[74:75], v[76:77]
	v_pk_fma_f32 v[78:79], v[16:17], v[74:75], v[72:73]
	ds_read_b128 v[72:75], v103 offset:56320
	s_waitcnt lgkmcnt(0)
	v_pk_fma_f32 v[76:77], v[54:55], v[72:73], v[76:77]
	v_pk_fma_f32 v[72:73], v[12:13], v[72:73], v[78:79]
	v_pk_fma_f32 v[76:77], v[52:53], v[74:75], v[76:77]
	v_pk_fma_f32 v[72:73], v[10:11], v[74:75], v[72:73]
	v_add_f32_e32 v88, v76, v77
	v_add_f32_e32 v72, v72, v73
	ds_read_b128 v[74:77], v103 offset:57344
	s_waitcnt lgkmcnt(0)
	v_pk_fma_f32 v[78:79], v[4:5], v[74:75], 0 op_sel_hi:[1,1,0]
	v_pk_fma_f32 v[74:75], v[58:59], v[74:75], 0 op_sel_hi:[1,1,0]
	v_pk_fma_f32 v[78:79], v[2:3], v[76:77], v[78:79]
	v_pk_fma_f32 v[96:97], v[56:57], v[76:77], v[74:75]
	ds_read_b128 v[74:77], v103 offset:58368
	s_waitcnt lgkmcnt(0)
	v_pk_fma_f32 v[78:79], v[8:9], v[74:75], v[78:79]
	v_pk_fma_f32 v[74:75], v[66:67], v[74:75], v[96:97]
	v_pk_fma_f32 v[78:79], v[6:7], v[76:77], v[78:79]
	v_pk_fma_f32 v[96:97], v[62:63], v[76:77], v[74:75]
	ds_read_b128 v[74:77], v103 offset:59392
	s_waitcnt lgkmcnt(0)
	v_pk_fma_f32 v[78:79], v[34:35], v[74:75], v[78:79]
	v_pk_fma_f32 v[74:75], v[70:71], v[74:75], v[96:97]
	v_pk_fma_f32 v[78:79], v[32:33], v[76:77], v[78:79]
	v_pk_fma_f32 v[96:97], v[68:69], v[76:77], v[74:75]
	ds_read_b128 v[74:77], v103 offset:60416
	s_waitcnt lgkmcnt(0)
	v_pk_fma_f32 v[78:79], v[38:39], v[74:75], v[78:79]
	v_pk_fma_f32 v[74:75], v[30:31], v[74:75], v[96:97]
	v_pk_fma_f32 v[78:79], v[36:37], v[76:77], v[78:79]
	v_pk_fma_f32 v[96:97], v[28:29], v[76:77], v[74:75]
	ds_read_b128 v[74:77], v103 offset:61440
	s_waitcnt lgkmcnt(0)
	v_pk_fma_f32 v[78:79], v[42:43], v[74:75], v[78:79]
	v_pk_fma_f32 v[74:75], v[22:23], v[74:75], v[96:97]
	v_pk_fma_f32 v[78:79], v[40:41], v[76:77], v[78:79]
	v_pk_fma_f32 v[96:97], v[20:21], v[76:77], v[74:75]
	ds_read_b128 v[74:77], v103 offset:62464
	s_waitcnt lgkmcnt(0)
	v_pk_fma_f32 v[78:79], v[46:47], v[74:75], v[78:79]
	v_pk_fma_f32 v[74:75], v[26:27], v[74:75], v[96:97]
	v_pk_fma_f32 v[78:79], v[44:45], v[76:77], v[78:79]
	v_pk_fma_f32 v[96:97], v[24:25], v[76:77], v[74:75]
	ds_read_b128 v[74:77], v103 offset:63488
	s_waitcnt lgkmcnt(0)
	v_pk_fma_f32 v[78:79], v[50:51], v[74:75], v[78:79]
	v_pk_fma_f32 v[74:75], v[18:19], v[74:75], v[96:97]
	v_pk_fma_f32 v[78:79], v[48:49], v[76:77], v[78:79]
	v_pk_fma_f32 v[96:97], v[16:17], v[76:77], v[74:75]
	ds_read_b128 v[74:77], v103 offset:64512
	s_waitcnt lgkmcnt(0)
	v_pk_fma_f32 v[78:79], v[54:55], v[74:75], v[78:79]
	v_pk_fma_f32 v[74:75], v[12:13], v[74:75], v[96:97]
	v_pk_fma_f32 v[78:79], v[52:53], v[76:77], v[78:79]
	v_pk_fma_f32 v[74:75], v[10:11], v[76:77], v[74:75]
	v_add_f32_e32 v89, v78, v79
	v_add_f32_e32 v73, v74, v75
	v_add_u32_e32 v74, 0x10000, v103
	ds_read_b128 v[74:77], v74
	s_waitcnt lgkmcnt(0)
	v_pk_fma_f32 v[78:79], v[4:5], v[74:75], 0 op_sel_hi:[1,1,0]
	v_pk_fma_f32 v[74:75], v[58:59], v[74:75], 0 op_sel_hi:[1,1,0]
	v_pk_fma_f32 v[78:79], v[2:3], v[76:77], v[78:79]
	v_pk_fma_f32 v[96:97], v[56:57], v[76:77], v[74:75]
	v_add_u32_e32 v74, 0x10400, v103
	ds_read_b128 v[74:77], v74
	s_waitcnt lgkmcnt(0)
	v_pk_fma_f32 v[78:79], v[8:9], v[74:75], v[78:79]
	v_pk_fma_f32 v[74:75], v[66:67], v[74:75], v[96:97]
	v_pk_fma_f32 v[78:79], v[6:7], v[76:77], v[78:79]
	v_pk_fma_f32 v[96:97], v[62:63], v[76:77], v[74:75]
	v_add_u32_e32 v74, 0x10800, v103
	ds_read_b128 v[74:77], v74
	s_waitcnt lgkmcnt(0)
	v_pk_fma_f32 v[78:79], v[34:35], v[74:75], v[78:79]
	v_pk_fma_f32 v[74:75], v[70:71], v[74:75], v[96:97]
	v_pk_fma_f32 v[78:79], v[32:33], v[76:77], v[78:79]
	v_pk_fma_f32 v[96:97], v[68:69], v[76:77], v[74:75]
	v_add_u32_e32 v74, 0x10c00, v103
	ds_read_b128 v[74:77], v74
	s_waitcnt lgkmcnt(0)
	v_pk_fma_f32 v[78:79], v[38:39], v[74:75], v[78:79]
	v_pk_fma_f32 v[74:75], v[30:31], v[74:75], v[96:97]
	v_pk_fma_f32 v[78:79], v[36:37], v[76:77], v[78:79]
	v_pk_fma_f32 v[96:97], v[28:29], v[76:77], v[74:75]
	v_add_u32_e32 v74, 0x11000, v103
	ds_read_b128 v[74:77], v74
	s_waitcnt lgkmcnt(0)
	v_pk_fma_f32 v[78:79], v[42:43], v[74:75], v[78:79]
	v_pk_fma_f32 v[74:75], v[22:23], v[74:75], v[96:97]
	v_pk_fma_f32 v[78:79], v[40:41], v[76:77], v[78:79]
	v_pk_fma_f32 v[96:97], v[20:21], v[76:77], v[74:75]
	v_add_u32_e32 v74, 0x11400, v103
	ds_read_b128 v[74:77], v74
	s_waitcnt lgkmcnt(0)
	v_pk_fma_f32 v[78:79], v[46:47], v[74:75], v[78:79]
	v_pk_fma_f32 v[74:75], v[26:27], v[74:75], v[96:97]
	v_pk_fma_f32 v[78:79], v[44:45], v[76:77], v[78:79]
	v_pk_fma_f32 v[96:97], v[24:25], v[76:77], v[74:75]
	v_add_u32_e32 v74, 0x11800, v103
	ds_read_b128 v[74:77], v74
	s_waitcnt lgkmcnt(0)
	v_pk_fma_f32 v[78:79], v[50:51], v[74:75], v[78:79]
	v_pk_fma_f32 v[74:75], v[18:19], v[74:75], v[96:97]
	v_pk_fma_f32 v[78:79], v[48:49], v[76:77], v[78:79]
	v_pk_fma_f32 v[96:97], v[16:17], v[76:77], v[74:75]
	v_add_u32_e32 v74, 0x11c00, v103
	ds_read_b128 v[74:77], v74
	s_waitcnt lgkmcnt(0)
	v_pk_fma_f32 v[78:79], v[54:55], v[74:75], v[78:79]
	v_pk_fma_f32 v[74:75], v[12:13], v[74:75], v[96:97]
	v_pk_fma_f32 v[78:79], v[52:53], v[76:77], v[78:79]
	v_pk_fma_f32 v[74:75], v[10:11], v[76:77], v[74:75]
	v_add_f32_e32 v96, v78, v79
	v_add_f32_e32 v74, v74, v75
	v_add_u32_e32 v75, 0x12000, v103
	ds_read_b128 v[76:79], v75
	v_add_u32_e32 v75, 0x12400, v103
	s_waitcnt lgkmcnt(0)
	v_pk_fma_f32 v[98:99], v[4:5], v[76:77], 0 op_sel_hi:[1,1,0]
	v_pk_fma_f32 v[76:77], v[58:59], v[76:77], 0 op_sel_hi:[1,1,0]
	v_pk_fma_f32 v[98:99], v[2:3], v[78:79], v[98:99]
	v_pk_fma_f32 v[100:101], v[56:57], v[78:79], v[76:77]
	ds_read_b128 v[76:79], v75
	v_add_u32_e32 v75, 0x12800, v103
	s_waitcnt lgkmcnt(0)
	v_pk_fma_f32 v[98:99], v[8:9], v[76:77], v[98:99]
	v_pk_fma_f32 v[76:77], v[66:67], v[76:77], v[100:101]
	v_pk_fma_f32 v[98:99], v[6:7], v[78:79], v[98:99]
	v_pk_fma_f32 v[100:101], v[62:63], v[78:79], v[76:77]
	ds_read_b128 v[76:79], v75
	v_add_u32_e32 v75, 0x12c00, v103
	s_waitcnt lgkmcnt(0)
	v_pk_fma_f32 v[98:99], v[34:35], v[76:77], v[98:99]
	v_pk_fma_f32 v[76:77], v[70:71], v[76:77], v[100:101]
	v_pk_fma_f32 v[98:99], v[32:33], v[78:79], v[98:99]
	v_pk_fma_f32 v[100:101], v[68:69], v[78:79], v[76:77]
	ds_read_b128 v[76:79], v75
	v_add_u32_e32 v75, 0x13000, v103
	s_waitcnt lgkmcnt(0)
	v_pk_fma_f32 v[98:99], v[38:39], v[76:77], v[98:99]
	v_pk_fma_f32 v[76:77], v[30:31], v[76:77], v[100:101]
	v_pk_fma_f32 v[98:99], v[36:37], v[78:79], v[98:99]
	v_pk_fma_f32 v[100:101], v[28:29], v[78:79], v[76:77]
	ds_read_b128 v[76:79], v75
	v_add_u32_e32 v75, 0x13400, v103
	s_waitcnt lgkmcnt(0)
	v_pk_fma_f32 v[98:99], v[42:43], v[76:77], v[98:99]
	v_pk_fma_f32 v[76:77], v[22:23], v[76:77], v[100:101]
	v_pk_fma_f32 v[98:99], v[40:41], v[78:79], v[98:99]
	v_pk_fma_f32 v[100:101], v[20:21], v[78:79], v[76:77]
	ds_read_b128 v[76:79], v75
	v_add_u32_e32 v75, 0x13800, v103
	s_waitcnt lgkmcnt(0)
	v_pk_fma_f32 v[98:99], v[46:47], v[76:77], v[98:99]
	v_pk_fma_f32 v[76:77], v[26:27], v[76:77], v[100:101]
	v_pk_fma_f32 v[98:99], v[44:45], v[78:79], v[98:99]
	v_pk_fma_f32 v[100:101], v[24:25], v[78:79], v[76:77]
	ds_read_b128 v[76:79], v75
	v_add_u32_e32 v75, 0x13c00, v103
	s_waitcnt lgkmcnt(0)
	v_pk_fma_f32 v[98:99], v[50:51], v[76:77], v[98:99]
	v_pk_fma_f32 v[76:77], v[18:19], v[76:77], v[100:101]
	v_pk_fma_f32 v[98:99], v[48:49], v[78:79], v[98:99]
	v_pk_fma_f32 v[100:101], v[16:17], v[78:79], v[76:77]
	ds_read_b128 v[76:79], v75
	s_waitcnt lgkmcnt(0)
	v_pk_fma_f32 v[98:99], v[54:55], v[76:77], v[98:99]
	v_pk_fma_f32 v[76:77], v[12:13], v[76:77], v[100:101]
	v_pk_fma_f32 v[98:99], v[52:53], v[78:79], v[98:99]
	v_pk_fma_f32 v[76:77], v[10:11], v[78:79], v[76:77]
	v_add_f32_e32 v97, v98, v99
	v_add_f32_e32 v75, v76, v77
	v_add_u32_e32 v76, 0x14000, v103
	ds_read_b128 v[76:79], v76
	s_waitcnt lgkmcnt(0)
	v_pk_fma_f32 v[98:99], v[4:5], v[76:77], 0 op_sel_hi:[1,1,0]
	v_pk_fma_f32 v[76:77], v[58:59], v[76:77], 0 op_sel_hi:[1,1,0]
	v_pk_fma_f32 v[98:99], v[2:3], v[78:79], v[98:99]
	v_pk_fma_f32 v[100:101], v[56:57], v[78:79], v[76:77]
	v_add_u32_e32 v76, 0x14400, v103
	ds_read_b128 v[76:79], v76
	s_waitcnt lgkmcnt(0)
	v_pk_fma_f32 v[98:99], v[8:9], v[76:77], v[98:99]
	v_pk_fma_f32 v[76:77], v[66:67], v[76:77], v[100:101]
	v_pk_fma_f32 v[98:99], v[6:7], v[78:79], v[98:99]
	v_pk_fma_f32 v[100:101], v[62:63], v[78:79], v[76:77]
	v_add_u32_e32 v76, 0x14800, v103
	ds_read_b128 v[76:79], v76
	s_waitcnt lgkmcnt(0)
	v_pk_fma_f32 v[98:99], v[34:35], v[76:77], v[98:99]
	v_pk_fma_f32 v[76:77], v[70:71], v[76:77], v[100:101]
	v_pk_fma_f32 v[98:99], v[32:33], v[78:79], v[98:99]
	v_pk_fma_f32 v[100:101], v[68:69], v[78:79], v[76:77]
	v_add_u32_e32 v76, 0x14c00, v103
	ds_read_b128 v[76:79], v76
	s_waitcnt lgkmcnt(0)
	v_pk_fma_f32 v[98:99], v[38:39], v[76:77], v[98:99]
	v_pk_fma_f32 v[76:77], v[30:31], v[76:77], v[100:101]
	v_pk_fma_f32 v[98:99], v[36:37], v[78:79], v[98:99]
	v_pk_fma_f32 v[100:101], v[28:29], v[78:79], v[76:77]
	v_add_u32_e32 v76, 0x15000, v103
	ds_read_b128 v[76:79], v76
	s_waitcnt lgkmcnt(0)
	v_pk_fma_f32 v[98:99], v[42:43], v[76:77], v[98:99]
	v_pk_fma_f32 v[76:77], v[22:23], v[76:77], v[100:101]
	v_pk_fma_f32 v[98:99], v[40:41], v[78:79], v[98:99]
	v_pk_fma_f32 v[100:101], v[20:21], v[78:79], v[76:77]
	v_add_u32_e32 v76, 0x15400, v103
	ds_read_b128 v[76:79], v76
	s_waitcnt lgkmcnt(0)
	v_pk_fma_f32 v[98:99], v[46:47], v[76:77], v[98:99]
	v_pk_fma_f32 v[76:77], v[26:27], v[76:77], v[100:101]
	v_pk_fma_f32 v[98:99], v[44:45], v[78:79], v[98:99]
	v_pk_fma_f32 v[100:101], v[24:25], v[78:79], v[76:77]
	v_add_u32_e32 v76, 0x15800, v103
	ds_read_b128 v[76:79], v76
	s_waitcnt lgkmcnt(0)
	v_pk_fma_f32 v[98:99], v[50:51], v[76:77], v[98:99]
	v_pk_fma_f32 v[76:77], v[18:19], v[76:77], v[100:101]
	v_pk_fma_f32 v[98:99], v[48:49], v[78:79], v[98:99]
	v_pk_fma_f32 v[100:101], v[16:17], v[78:79], v[76:77]
	v_add_u32_e32 v76, 0x15c00, v103
	ds_read_b128 v[76:79], v76
	s_waitcnt lgkmcnt(0)
	v_pk_fma_f32 v[98:99], v[54:55], v[76:77], v[98:99]
	v_pk_fma_f32 v[76:77], v[12:13], v[76:77], v[100:101]
	v_pk_fma_f32 v[98:99], v[52:53], v[78:79], v[98:99]
	v_pk_fma_f32 v[76:77], v[10:11], v[78:79], v[76:77]
	v_add_f32_e32 v98, v98, v99
	v_add_f32_e32 v76, v76, v77
	v_add_u32_e32 v77, 0x16000, v103
	ds_read_b128 v[104:107], v77
	v_add_u32_e32 v77, 0x16400, v103
	s_waitcnt lgkmcnt(0)
	v_pk_fma_f32 v[78:79], v[4:5], v[104:105], 0 op_sel_hi:[1,1,0]
	v_pk_fma_f32 v[100:101], v[58:59], v[104:105], 0 op_sel_hi:[1,1,0]
	v_pk_fma_f32 v[78:79], v[2:3], v[106:107], v[78:79]
	v_pk_fma_f32 v[100:101], v[56:57], v[106:107], v[100:101]
	ds_read_b128 v[104:107], v77
	v_add_u32_e32 v77, 0x16800, v103
	s_waitcnt lgkmcnt(0)
	v_pk_fma_f32 v[78:79], v[8:9], v[104:105], v[78:79]
	v_pk_fma_f32 v[100:101], v[66:67], v[104:105], v[100:101]
	v_pk_fma_f32 v[78:79], v[6:7], v[106:107], v[78:79]
	v_pk_fma_f32 v[100:101], v[62:63], v[106:107], v[100:101]
	ds_read_b128 v[104:107], v77
	v_add_u32_e32 v77, 0x16c00, v103
	s_waitcnt lgkmcnt(0)
	v_pk_fma_f32 v[78:79], v[34:35], v[104:105], v[78:79]
	v_pk_fma_f32 v[100:101], v[70:71], v[104:105], v[100:101]
	v_pk_fma_f32 v[78:79], v[32:33], v[106:107], v[78:79]
	v_pk_fma_f32 v[100:101], v[68:69], v[106:107], v[100:101]
	ds_read_b128 v[104:107], v77
	v_add_u32_e32 v77, 0x17000, v103
	s_waitcnt lgkmcnt(0)
	v_pk_fma_f32 v[78:79], v[38:39], v[104:105], v[78:79]
	v_pk_fma_f32 v[100:101], v[30:31], v[104:105], v[100:101]
	v_pk_fma_f32 v[78:79], v[36:37], v[106:107], v[78:79]
	v_pk_fma_f32 v[100:101], v[28:29], v[106:107], v[100:101]
	ds_read_b128 v[104:107], v77
	v_add_u32_e32 v77, 0x17400, v103
	s_waitcnt lgkmcnt(0)
	v_pk_fma_f32 v[78:79], v[42:43], v[104:105], v[78:79]
	v_pk_fma_f32 v[100:101], v[22:23], v[104:105], v[100:101]
	v_pk_fma_f32 v[78:79], v[40:41], v[106:107], v[78:79]
	v_pk_fma_f32 v[100:101], v[20:21], v[106:107], v[100:101]
	ds_read_b128 v[104:107], v77
	v_add_u32_e32 v77, 0x17800, v103
	s_waitcnt lgkmcnt(0)
	v_pk_fma_f32 v[78:79], v[46:47], v[104:105], v[78:79]
	v_pk_fma_f32 v[100:101], v[26:27], v[104:105], v[100:101]
	v_pk_fma_f32 v[78:79], v[44:45], v[106:107], v[78:79]
	v_pk_fma_f32 v[100:101], v[24:25], v[106:107], v[100:101]
	ds_read_b128 v[104:107], v77
	v_add_u32_e32 v77, 0x17c00, v103
	s_waitcnt lgkmcnt(0)
	v_pk_fma_f32 v[78:79], v[50:51], v[104:105], v[78:79]
	v_pk_fma_f32 v[100:101], v[18:19], v[104:105], v[100:101]
	v_pk_fma_f32 v[78:79], v[48:49], v[106:107], v[78:79]
	v_pk_fma_f32 v[100:101], v[16:17], v[106:107], v[100:101]
	ds_read_b128 v[104:107], v77
	s_waitcnt lgkmcnt(0)
	v_pk_fma_f32 v[78:79], v[54:55], v[104:105], v[78:79]
	v_pk_fma_f32 v[100:101], v[12:13], v[104:105], v[100:101]
	v_pk_fma_f32 v[78:79], v[52:53], v[106:107], v[78:79]
	v_pk_fma_f32 v[100:101], v[10:11], v[106:107], v[100:101]
	v_add_f32_e32 v99, v78, v79
	v_add_f32_e32 v77, v100, v101
	v_add_u32_e32 v78, 0x18000, v103
	ds_read_b128 v[104:107], v78
	s_waitcnt lgkmcnt(0)
	v_pk_fma_f32 v[78:79], v[4:5], v[104:105], 0 op_sel_hi:[1,1,0]
	v_pk_fma_f32 v[100:101], v[58:59], v[104:105], 0 op_sel_hi:[1,1,0]
	v_pk_fma_f32 v[78:79], v[2:3], v[106:107], v[78:79]
	v_pk_fma_f32 v[100:101], v[56:57], v[106:107], v[100:101]
	ds_read_b128 v[104:107], v80
	v_add_u32_e32 v80, 0x18800, v103
	s_waitcnt lgkmcnt(0)
	v_pk_fma_f32 v[78:79], v[8:9], v[104:105], v[78:79]
	v_pk_fma_f32 v[100:101], v[66:67], v[104:105], v[100:101]
	v_pk_fma_f32 v[78:79], v[6:7], v[106:107], v[78:79]
	v_pk_fma_f32 v[100:101], v[62:63], v[106:107], v[100:101]
	ds_read_b128 v[104:107], v80
	v_add_u32_e32 v80, 0x18c00, v103
	s_waitcnt lgkmcnt(0)
	v_pk_fma_f32 v[78:79], v[34:35], v[104:105], v[78:79]
	v_pk_fma_f32 v[100:101], v[70:71], v[104:105], v[100:101]
	v_pk_fma_f32 v[78:79], v[32:33], v[106:107], v[78:79]
	v_pk_fma_f32 v[100:101], v[68:69], v[106:107], v[100:101]
	ds_read_b128 v[104:107], v80
	v_add_u32_e32 v80, 0x19000, v103
	s_waitcnt lgkmcnt(0)
	v_pk_fma_f32 v[78:79], v[38:39], v[104:105], v[78:79]
	v_pk_fma_f32 v[100:101], v[30:31], v[104:105], v[100:101]
	v_pk_fma_f32 v[78:79], v[36:37], v[106:107], v[78:79]
	v_pk_fma_f32 v[100:101], v[28:29], v[106:107], v[100:101]
	ds_read_b128 v[104:107], v80
	v_add_u32_e32 v80, 0x19400, v103
	s_waitcnt lgkmcnt(0)
	v_pk_fma_f32 v[78:79], v[42:43], v[104:105], v[78:79]
	v_pk_fma_f32 v[100:101], v[22:23], v[104:105], v[100:101]
	v_pk_fma_f32 v[78:79], v[40:41], v[106:107], v[78:79]
	v_pk_fma_f32 v[100:101], v[20:21], v[106:107], v[100:101]
	ds_read_b128 v[104:107], v80
	v_add_u32_e32 v80, 0x19800, v103
	s_waitcnt lgkmcnt(0)
	v_pk_fma_f32 v[78:79], v[46:47], v[104:105], v[78:79]
	v_pk_fma_f32 v[100:101], v[26:27], v[104:105], v[100:101]
	v_pk_fma_f32 v[78:79], v[44:45], v[106:107], v[78:79]
	v_pk_fma_f32 v[100:101], v[24:25], v[106:107], v[100:101]
	ds_read_b128 v[104:107], v80
	v_add_u32_e32 v80, 0x19c00, v103
	s_waitcnt lgkmcnt(0)
	v_pk_fma_f32 v[78:79], v[50:51], v[104:105], v[78:79]
	v_pk_fma_f32 v[100:101], v[18:19], v[104:105], v[100:101]
	v_pk_fma_f32 v[78:79], v[48:49], v[106:107], v[78:79]
	v_pk_fma_f32 v[100:101], v[16:17], v[106:107], v[100:101]
	ds_read_b128 v[104:107], v80
	v_add_u32_e32 v80, 0x1c000, v103
	s_waitcnt lgkmcnt(0)
	v_pk_fma_f32 v[78:79], v[54:55], v[104:105], v[78:79]
	v_pk_fma_f32 v[100:101], v[12:13], v[104:105], v[100:101]
	v_pk_fma_f32 v[78:79], v[52:53], v[106:107], v[78:79]
	v_pk_fma_f32 v[104:105], v[10:11], v[106:107], v[100:101]
	v_add_f32_e32 v100, v78, v79
	v_add_f32_e32 v78, v104, v105
	v_add_u32_e32 v79, 0x1a000, v103
	ds_read_b128 v[104:107], v79
	v_add_u32_e32 v79, 0x1a400, v103
	s_waitcnt lgkmcnt(0)
	v_pk_fma_f32 v[108:109], v[4:5], v[104:105], 0 op_sel_hi:[1,1,0]
	v_pk_fma_f32 v[104:105], v[58:59], v[104:105], 0 op_sel_hi:[1,1,0]
	v_pk_fma_f32 v[108:109], v[2:3], v[106:107], v[108:109]
	v_pk_fma_f32 v[110:111], v[56:57], v[106:107], v[104:105]
	ds_read_b128 v[104:107], v79
	v_add_u32_e32 v79, 0x1a800, v103
	s_waitcnt lgkmcnt(0)
	v_pk_fma_f32 v[108:109], v[8:9], v[104:105], v[108:109]
	v_pk_fma_f32 v[104:105], v[66:67], v[104:105], v[110:111]
	v_pk_fma_f32 v[108:109], v[6:7], v[106:107], v[108:109]
	v_pk_fma_f32 v[110:111], v[62:63], v[106:107], v[104:105]
	ds_read_b128 v[104:107], v79
	v_add_u32_e32 v79, 0x1ac00, v103
	s_waitcnt lgkmcnt(0)
	v_pk_fma_f32 v[108:109], v[34:35], v[104:105], v[108:109]
	v_pk_fma_f32 v[104:105], v[70:71], v[104:105], v[110:111]
	v_pk_fma_f32 v[108:109], v[32:33], v[106:107], v[108:109]
	v_pk_fma_f32 v[110:111], v[68:69], v[106:107], v[104:105]
	ds_read_b128 v[104:107], v79
	v_add_u32_e32 v79, 0x1b000, v103
	s_waitcnt lgkmcnt(0)
	v_pk_fma_f32 v[108:109], v[38:39], v[104:105], v[108:109]
	v_pk_fma_f32 v[104:105], v[30:31], v[104:105], v[110:111]
	v_pk_fma_f32 v[108:109], v[36:37], v[106:107], v[108:109]
	v_pk_fma_f32 v[110:111], v[28:29], v[106:107], v[104:105]
	ds_read_b128 v[104:107], v79
	v_add_u32_e32 v79, 0x1b400, v103
	s_waitcnt lgkmcnt(0)
	v_pk_fma_f32 v[108:109], v[42:43], v[104:105], v[108:109]
	v_pk_fma_f32 v[104:105], v[22:23], v[104:105], v[110:111]
	v_pk_fma_f32 v[108:109], v[40:41], v[106:107], v[108:109]
	v_pk_fma_f32 v[110:111], v[20:21], v[106:107], v[104:105]
	ds_read_b128 v[104:107], v79
	v_add_u32_e32 v79, 0x1b800, v103
	s_waitcnt lgkmcnt(0)
	v_pk_fma_f32 v[108:109], v[46:47], v[104:105], v[108:109]
	v_pk_fma_f32 v[104:105], v[26:27], v[104:105], v[110:111]
	v_pk_fma_f32 v[108:109], v[44:45], v[106:107], v[108:109]
	v_pk_fma_f32 v[110:111], v[24:25], v[106:107], v[104:105]
	ds_read_b128 v[104:107], v79
	v_add_u32_e32 v79, 0x1bc00, v103
	s_waitcnt lgkmcnt(0)
	v_pk_fma_f32 v[108:109], v[50:51], v[104:105], v[108:109]
	v_pk_fma_f32 v[104:105], v[18:19], v[104:105], v[110:111]
	v_pk_fma_f32 v[108:109], v[48:49], v[106:107], v[108:109]
	v_pk_fma_f32 v[110:111], v[16:17], v[106:107], v[104:105]
	ds_read_b128 v[104:107], v79
	s_waitcnt lgkmcnt(0)
	v_pk_fma_f32 v[108:109], v[54:55], v[104:105], v[108:109]
	v_pk_fma_f32 v[104:105], v[12:13], v[104:105], v[110:111]
	v_pk_fma_f32 v[108:109], v[52:53], v[106:107], v[108:109]
	v_pk_fma_f32 v[104:105], v[10:11], v[106:107], v[104:105]
	v_add_f32_e32 v101, v108, v109
	v_add_f32_e32 v79, v104, v105
	ds_read_b128 v[104:107], v80
	v_add_u32_e32 v80, 0x1c400, v103
	s_waitcnt lgkmcnt(0)
	v_pk_fma_f32 v[108:109], v[4:5], v[104:105], 0 op_sel_hi:[1,1,0]
	v_pk_fma_f32 v[104:105], v[58:59], v[104:105], 0 op_sel_hi:[1,1,0]
	v_pk_fma_f32 v[108:109], v[2:3], v[106:107], v[108:109]
	v_pk_fma_f32 v[110:111], v[56:57], v[106:107], v[104:105]
	ds_read_b128 v[104:107], v80
	v_add_u32_e32 v80, 0x1c800, v103
	s_waitcnt lgkmcnt(0)
	v_pk_fma_f32 v[108:109], v[8:9], v[104:105], v[108:109]
	v_pk_fma_f32 v[104:105], v[66:67], v[104:105], v[110:111]
	v_pk_fma_f32 v[108:109], v[6:7], v[106:107], v[108:109]
	v_pk_fma_f32 v[110:111], v[62:63], v[106:107], v[104:105]
	ds_read_b128 v[104:107], v80
	v_add_u32_e32 v80, 0x1cc00, v103
	s_waitcnt lgkmcnt(0)
	v_pk_fma_f32 v[108:109], v[34:35], v[104:105], v[108:109]
	v_pk_fma_f32 v[104:105], v[70:71], v[104:105], v[110:111]
	v_pk_fma_f32 v[108:109], v[32:33], v[106:107], v[108:109]
	v_pk_fma_f32 v[110:111], v[68:69], v[106:107], v[104:105]
	ds_read_b128 v[104:107], v80
	v_add_u32_e32 v80, 0x1d000, v103
	s_waitcnt lgkmcnt(0)
	v_pk_fma_f32 v[108:109], v[38:39], v[104:105], v[108:109]
	v_pk_fma_f32 v[104:105], v[30:31], v[104:105], v[110:111]
	v_pk_fma_f32 v[108:109], v[36:37], v[106:107], v[108:109]
	v_pk_fma_f32 v[110:111], v[28:29], v[106:107], v[104:105]
	ds_read_b128 v[104:107], v80
	v_add_u32_e32 v80, 0x1d400, v103
	s_waitcnt lgkmcnt(0)
	v_pk_fma_f32 v[108:109], v[42:43], v[104:105], v[108:109]
	v_pk_fma_f32 v[104:105], v[22:23], v[104:105], v[110:111]
	v_pk_fma_f32 v[108:109], v[40:41], v[106:107], v[108:109]
	v_pk_fma_f32 v[110:111], v[20:21], v[106:107], v[104:105]
	ds_read_b128 v[104:107], v80
	v_add_u32_e32 v80, 0x1d800, v103
	s_waitcnt lgkmcnt(0)
	v_pk_fma_f32 v[108:109], v[46:47], v[104:105], v[108:109]
	v_pk_fma_f32 v[104:105], v[26:27], v[104:105], v[110:111]
	v_pk_fma_f32 v[108:109], v[44:45], v[106:107], v[108:109]
	v_pk_fma_f32 v[110:111], v[24:25], v[106:107], v[104:105]
	ds_read_b128 v[104:107], v80
	v_add_u32_e32 v80, 0x1dc00, v103
	s_waitcnt lgkmcnt(0)
	v_pk_fma_f32 v[108:109], v[50:51], v[104:105], v[108:109]
	v_pk_fma_f32 v[104:105], v[18:19], v[104:105], v[110:111]
	v_pk_fma_f32 v[108:109], v[48:49], v[106:107], v[108:109]
	v_pk_fma_f32 v[110:111], v[16:17], v[106:107], v[104:105]
	ds_read_b128 v[104:107], v80
	s_waitcnt lgkmcnt(0)
	v_pk_fma_f32 v[108:109], v[54:55], v[104:105], v[108:109]
	v_pk_fma_f32 v[104:105], v[12:13], v[104:105], v[110:111]
	v_pk_fma_f32 v[108:109], v[52:53], v[106:107], v[108:109]
	v_pk_fma_f32 v[104:105], v[10:11], v[106:107], v[104:105]
	v_add_f32_e32 v102, v108, v109
	v_add_f32_e32 v80, v104, v105
	v_add_u32_e32 v104, 0x1e000, v103
	ds_read_b128 v[104:107], v104
	s_waitcnt lgkmcnt(0)
	v_pk_fma_f32 v[4:5], v[4:5], v[104:105], 0 op_sel_hi:[1,1,0]
	s_nop 0
	v_pk_fma_f32 v[108:109], v[2:3], v[106:107], v[4:5]
	v_pk_fma_f32 v[2:3], v[58:59], v[104:105], 0 op_sel_hi:[1,1,0]
	s_nop 0
	v_pk_fma_f32 v[56:57], v[56:57], v[106:107], v[2:3]
	v_add_u32_e32 v2, 0x1e400, v103
	ds_read_b128 v[2:5], v2
	s_waitcnt lgkmcnt(0)
	v_pk_fma_f32 v[8:9], v[8:9], v[2:3], v[108:109]
	v_pk_fma_f32 v[2:3], v[66:67], v[2:3], v[56:57]
	v_pk_fma_f32 v[6:7], v[6:7], v[4:5], v[8:9]
	v_pk_fma_f32 v[8:9], v[62:63], v[4:5], v[2:3]
	v_add_u32_e32 v2, 0x1e800, v103
	ds_read_b128 v[2:5], v2
	s_waitcnt lgkmcnt(0)
	v_pk_fma_f32 v[6:7], v[34:35], v[2:3], v[6:7]
	v_pk_fma_f32 v[2:3], v[70:71], v[2:3], v[8:9]
	v_pk_fma_f32 v[6:7], v[32:33], v[4:5], v[6:7]
	v_pk_fma_f32 v[8:9], v[68:69], v[4:5], v[2:3]
	v_add_u32_e32 v2, 0x1ec00, v103
	ds_read_b128 v[2:5], v2
	s_waitcnt lgkmcnt(0)
	v_pk_fma_f32 v[6:7], v[38:39], v[2:3], v[6:7]
	v_pk_fma_f32 v[2:3], v[30:31], v[2:3], v[8:9]
	v_pk_fma_f32 v[6:7], v[36:37], v[4:5], v[6:7]
	v_pk_fma_f32 v[8:9], v[28:29], v[4:5], v[2:3]
	v_add_u32_e32 v2, 0x1f000, v103
	ds_read_b128 v[2:5], v2
	s_waitcnt lgkmcnt(0)
	v_pk_fma_f32 v[6:7], v[42:43], v[2:3], v[6:7]
	v_pk_fma_f32 v[2:3], v[22:23], v[2:3], v[8:9]
	v_pk_fma_f32 v[6:7], v[40:41], v[4:5], v[6:7]
	v_pk_fma_f32 v[8:9], v[20:21], v[4:5], v[2:3]
	v_add_u32_e32 v2, 0x1f400, v103
	ds_read_b128 v[2:5], v2
	s_waitcnt lgkmcnt(0)
	v_pk_fma_f32 v[6:7], v[46:47], v[2:3], v[6:7]
	v_pk_fma_f32 v[2:3], v[26:27], v[2:3], v[8:9]
	v_pk_fma_f32 v[6:7], v[44:45], v[4:5], v[6:7]
	v_pk_fma_f32 v[8:9], v[24:25], v[4:5], v[2:3]
	v_add_u32_e32 v2, 0x1f800, v103
	ds_read_b128 v[2:5], v2
	s_waitcnt lgkmcnt(0)
	v_pk_fma_f32 v[6:7], v[50:51], v[2:3], v[6:7]
	v_pk_fma_f32 v[2:3], v[18:19], v[2:3], v[8:9]
	v_pk_fma_f32 v[6:7], v[48:49], v[4:5], v[6:7]
	v_pk_fma_f32 v[8:9], v[16:17], v[4:5], v[2:3]
	v_add_u32_e32 v2, 0x1fc00, v103
	ds_read_b128 v[2:5], v2
	s_waitcnt lgkmcnt(0)
	v_pk_fma_f32 v[6:7], v[54:55], v[2:3], v[6:7]
	v_pk_fma_f32 v[2:3], v[12:13], v[2:3], v[8:9]
	v_pk_fma_f32 v[6:7], v[52:53], v[4:5], v[6:7]
	v_pk_fma_f32 v[4:5], v[10:11], v[4:5], v[2:3]
	v_and_b32_e32 v3, 32, v1
	v_cmp_eq_u32_e32 vcc, 0, v3
	v_add_f32_e32 v4, v4, v5
	v_add_f32_e32 v2, v6, v7
	v_cndmask_b32_e32 v5, v81, v96, vcc
	ds_bpermute_b32 v5, v95, v5
	v_cndmask_b32_e32 v6, v82, v97, vcc
	ds_bpermute_b32 v6, v95, v6
	v_cndmask_b32_e32 v7, v84, v98, vcc
	ds_bpermute_b32 v7, v95, v7
	v_cndmask_b32_e32 v8, v85, v99, vcc
	ds_bpermute_b32 v8, v95, v8
	v_cndmask_b32_e32 v9, v86, v100, vcc
	v_cndmask_b32_e32 v3, v96, v81, vcc
	ds_bpermute_b32 v9, v95, v9
	v_cndmask_b32_e32 v10, v87, v101, vcc
	s_waitcnt lgkmcnt(4)
	v_add_f32_e32 v3, v3, v5
	v_cndmask_b32_e32 v5, v97, v82, vcc
	ds_bpermute_b32 v10, v95, v10
	v_cndmask_b32_e32 v11, v88, v102, vcc
	s_waitcnt lgkmcnt(4)
	v_add_f32_e32 v6, v5, v6
	v_cndmask_b32_e32 v5, v98, v84, vcc
	ds_bpermute_b32 v11, v95, v11
	s_waitcnt lgkmcnt(4)
	v_add_f32_e32 v7, v5, v7
	v_cndmask_b32_e32 v5, v99, v85, vcc
	s_waitcnt lgkmcnt(3)
	v_add_f32_e32 v8, v5, v8
	v_cndmask_b32_e32 v5, v100, v86, vcc
	s_waitcnt lgkmcnt(2)
	v_add_f32_e32 v5, v5, v9
	v_cndmask_b32_e32 v9, v101, v87, vcc
	s_waitcnt lgkmcnt(1)
	v_add_f32_e32 v9, v9, v10
	v_cndmask_b32_e32 v10, v102, v88, vcc
	s_waitcnt lgkmcnt(0)
	v_add_f32_e32 v10, v10, v11
	v_cndmask_b32_e32 v11, v2, v89, vcc
	v_cndmask_b32_e32 v2, v89, v2, vcc
	ds_bpermute_b32 v2, v95, v2
	s_waitcnt lgkmcnt(0)
	v_add_f32_e32 v11, v11, v2
	v_and_b32_e32 v2, 16, v1
	v_cmp_eq_u32_e64 s[10:11], 0, v2
	s_nop 1
	v_cndmask_b32_e64 v2, v5, v3, s[10:11]
	v_cndmask_b32_e64 v3, v3, v5, s[10:11]
	ds_bpermute_b32 v3, v94, v3
	s_waitcnt lgkmcnt(0)
	v_add_f32_e32 v5, v2, v3
	v_cndmask_b32_e64 v3, v6, v9, s[10:11]
	ds_bpermute_b32 v3, v94, v3
	v_cndmask_b32_e64 v2, v9, v6, s[10:11]
	v_cndmask_b32_e64 v6, v7, v10, s[10:11]
	ds_bpermute_b32 v6, v94, v6
	s_waitcnt lgkmcnt(1)
	v_add_f32_e32 v2, v2, v3
	v_cndmask_b32_e64 v3, v10, v7, s[10:11]
	v_cndmask_b32_e64 v7, v8, v11, s[10:11]
	ds_bpermute_b32 v7, v94, v7
	s_waitcnt lgkmcnt(1)
	v_add_f32_e32 v6, v3, v6
	v_cndmask_b32_e64 v3, v11, v8, s[10:11]
	s_waitcnt lgkmcnt(0)
	v_add_f32_e32 v3, v3, v7
	v_and_b32_e32 v7, 8, v1
	v_cmp_eq_u32_e64 s[12:13], 0, v7
	s_nop 1
	v_cndmask_b32_e64 v7, v6, v5, s[12:13]
	v_cndmask_b32_e64 v5, v5, v6, s[12:13]
	v_cndmask_b32_e64 v6, v3, v2, s[12:13]
	v_cndmask_b32_e64 v2, v2, v3, s[12:13]
	ds_bpermute_b32 v5, v93, v5
	ds_bpermute_b32 v2, v93, v2
	v_and_b32_e32 v3, 4, v1
	v_cmp_eq_u32_e64 s[14:15], 0, v3
	s_waitcnt lgkmcnt(1)
	v_add_f32_e32 v5, v7, v5
	s_waitcnt lgkmcnt(0)
	v_add_f32_e32 v2, v6, v2
	v_cndmask_b32_e64 v3, v2, v5, s[14:15]
	v_cndmask_b32_e64 v2, v5, v2, s[14:15]
	ds_bpermute_b32 v2, v92, v2
	v_and_b32_e32 v5, 3, v1
	v_bfe_u32 v1, v1, 2, 4
	v_cmp_eq_u32_e64 s[16:17], 0, v5
	v_lshlrev_b32_e32 v82, 2, v1
	s_waitcnt lgkmcnt(0)
	v_add_f32_e32 v2, v3, v2
	ds_bpermute_b32 v3, v91, v2
	s_waitcnt lgkmcnt(0)
	v_add_f32_e32 v2, v2, v3
	ds_bpermute_b32 v3, v90, v2
	s_and_saveexec_b64 s[40:41], s[16:17]
	s_cbranch_execz .LBB0_1749
	s_waitcnt lgkmcnt(0)
	v_add_f32_e32 v2, v2, v3
	global_load_dword v3, v82, s[38:39] offset:64
	v_cmp_lt_u32_e64 s[18:19], 7, v1
	s_waitcnt vmcnt(0)
	v_add_f32_e32 v5, v2, v3
	s_and_saveexec_b64 s[8:9], s[18:19]
	s_xor_b64 s[54:55], exec, s[8:9]
	s_cbranch_execz .LBB0_1746
	s_mov_b32 s18, 0xbfb8aa3b
	v_mul_f32_e64 v2, |v5|, s18
	v_exp_f32_e32 v6, v2
	s_lshl_b64 s[8:9], s[30:31], 5
	s_add_u32 s8, s58, s8
	s_addc_u32 s9, s59, s9
	v_lshl_add_u64 v[2:3], s[8:9], 0, v[82:83]
	v_add_f32_e32 v6, 1.0, v6
	s_mov_b32 s8, 0x800000
	v_cmp_gt_f32_e64 s[18:19], s8, v6
	s_movk_i32 s8, 0xffe0
	s_mov_b32 s9, -1
	v_cndmask_b32_e64 v7, 0, 32, s[18:19]
	v_ldexp_f32 v6, v6, v7
	v_log_f32_e32 v6, v6
	v_lshl_add_u64 v[2:3], v[2:3], 0, s[8:9]
	s_mov_b32 s8, 0x3f317217
	v_max_f32_e32 v5, v5, v5
	v_mul_f32_e32 v7, 0x3f317217, v6
	v_fma_f32 v7, v6, s8, -v7
	v_fmac_f32_e32 v7, 0x3377d1cf, v6
	s_mov_b32 s8, 0x7f800000
	v_fmac_f32_e32 v7, 0x3f317217, v6
	v_cmp_lt_f32_e64 s[20:21], |v6|, s8
	v_min_f32_e32 v5, 0, v5
	s_nop 0
	v_cndmask_b32_e64 v6, v6, v7, s[20:21]
	v_mov_b32_e32 v7, 0x41b17218
	v_cndmask_b32_e64 v7, 0, v7, s[18:19]
	v_sub_f32_e32 v6, v6, v7
	v_sub_f32_e32 v5, v5, v6
